# scan: waves w and w^4 paired (each computes one 32-row half over two dk blocks, bf16 state exchanged via LDS); 4 partials instead of 8
# baseline (speedup 1.0000x reference)
; __device__ __forceinline__ void phase_scan(const Args& a, unsigned char* smem, int tid, int lane, int wave) {
;     ...
;     for (int wu = blockIdx.x; wu < 256; wu += gridDim.x) {
;         const int combo = (wu & 7) * 2 + (wu >> 7), sl = (wu >> 3) & 15;
;         const int b = combo >> 3, h = (combo >> 1) & 3, dir = combo & 1;
;         const bf16_t* QE = (const bf16_t*)(a.ws + (dir ? WS_AZ : WS_BQ));
;         const bf16_t* KDT = (const bf16_t*)(a.ws + (dir ? WS_AVT : WS_AK));
;         const bf16_t* ATT = (const bf16_t*)(a.ws + WS_ATT) + (size_t)dir * 512 * 4 * 4096;
;         const float* DL = (const float*)(a.ws + WS_DL) + (size_t)dir * 520 * 1024;
;         const bf16_t* BVF = (const bf16_t*)(a.ws + WS_BVT) + (size_t)lane * 8;
;         bf16_t* O = (bf16_t*)((unsigned char*)a.out + (dir ? DO_OB : DO_OF));
;         f32x16 S;
; #pragma unroll
;         for (int i = 0; i < 16; ++i) S[i] = 0.f;
;         bf16x8 vB[4], qeA[4], atA; f32x4 dl[4];
;         bf16x8 nqe[4], nat;
;         u32x4 gcur = {0u, 0u, 0u, 0u}, gnxt = {0u, 0u, 0u, 0u};
;     ...
;         const unsigned char* scb; unsigned scsg;
;         { const int q16s = sl * 16 + (lane & 15);
;           if (wave == 5) { if (lane < 16) { scb = (const unsigned char*)KDT + (size_t)h * 32768 + (size_t)q16s * 128; scsg = 131072u; }
;                            else if (lane < 32) { scb = (const unsigned char*)QE + (size_t)h * 512 + (size_t)(q16s >> 2) * 2048 + (q16s & 3) * 128; scsg = 131072u; }
;                            else if (lane < 36) { scb = (const unsigned char*)ATT + (size_t)h * 8192 + (size_t)(sl * 4 + lane - 32) * 128; scsg = 32768u; }
;                            else { scb = (const unsigned char*)DL + (size_t)h * 1024 + (lane & 7) * 128; scsg = 4096u; } }
;           else if (wave == 6) { scb = (const unsigned char*)(a.ws + WS_BVT) + (size_t)(h * 16 + sl) * 4096 + (size_t)(lane & 31) * 128; scsg = 262144u; }
;           else { scb = (const unsigned char*)DL + (size_t)h * 1024; scsg = 0u; } }
;         unsigned scA = 0u, scB = 0u;
.Lscan_unit:
	s_and_b32 s40, s14, 7
	s_lshl_b32 s40, s40, 1
	s_lshr_b32 s41, s14, 7
	s_add_i32 s40, s40, s41
	s_lshr_b32 s18, s14, 3
	s_and_b32 s18, s18, 15
	s_lshr_b32 s15, s40, 3
	s_bfe_u32 s16, s40, 0x20001
	s_and_b32 s17, s40, 1
	s_cmp_eq_u32 s17, 1
	s_mov_b32 s41, 0x4200000
	s_cselect_b32 s41, 0x8300000, s41
	s_lshl_b32 s42, s16, 15
	s_add_u32 s41, s41, s42
	s_add_u32 s20, s94, s41
	s_addc_u32 s21, s95, 0
	s_cmp_eq_u32 s17, 1
	s_mov_b32 s41, 0x10501000
	s_cselect_b32 s41, 0xc401000, s41
	s_lshl_b32 s42, s16, 9
	s_add_u32 s41, s41, s42
	s_add_u32 s22, s94, s41
	s_addc_u32 s23, s95, 0
	s_lshl_b32 s41, s17, 24
	s_add_u32 s41, s41, 0x3a710000
	s_lshl_b32 s42, s16, 13
	s_add_u32 s41, s41, s42
	s_add_u32 s24, s94, s41
	s_addc_u32 s25, s95, 0
	s_mul_i32 s41, s17, 0x208000
	s_add_u32 s41, s41, 0x3c710000
	s_lshl_b32 s42, s16, 10
	s_add_u32 s41, s41, s42
	s_add_u32 s46, s94, s41
	s_addc_u32 s47, s95, 0
	s_lshl_b32 s41, s16, 4
	s_add_i32 s41, s41, s18
	s_lshl_b32 s41, s41, 12
	s_add_u32 s41, s41, 0x18700000
	s_add_u32 s48, s94, s41
	s_addc_u32 s49, s95, 0
	s_lshl_b32 s41, s17, 27
	s_add_u32 s26, s92, s41
	s_addc_u32 s27, s93, 0
	s_lshl_b32 s28, s15, 8
	s_cmp_eq_u32 s17, 1
	s_cselect_b32 s29, -1, 1
	s_cselect_b32 s41, 255, 0
	s_add_i32 s28, s28, s41
	s_cmp_lt_u32 s0, 5
	s_cselect_b32 s31, 4, 6
	v_lshrrev_b32_e32 v251, 5, v160
	v_and_b32_e32 v194, 31, v160
	v_lshlrev_b32_e32 v232, 11, v251
	v_lshl_add_u32 v232, v194, 4, v232
	s_lshl_b32 s41, s0, 14
	v_add_u32_e32 v232, s41, v232
	s_cmp_lt_u32 s0, 4
	s_cselect_b32 s41, 0, 8192
	s_cselect_b32 s42, 8192, 0
	v_add_u32_e32 v233, s42, v232
	v_add_u32_e32 v232, s41, v232
	v_xor_b32_e32 v233, 0x10000, v232
	v_lshlrev_b32_e32 v234, 4, v160
	s_lshl_b32 s41, s0, 12
	v_add_u32_e32 v235, s41, v234
	v_add_u32_e32 v246, 0x10000, v234
	s_and_b32 s42, s0, 3
	s_lshl_b32 s42, s42, 10
	v_add_u32_e32 v248, s42, v246
	s_lshl_b32 s41, s0, 10
	v_lshlrev_b32_e32 v247, 4, v251
	s_lshl_b32 s42, s0, 7
	s_add_i32 s42, s42, 0x12000
	v_add_u32_e32 v247, s42, v247
	s_cmp_lt_u32 s0, 4
	s_cbranch_scc0 .Lscan_stw_ge4
	v_add_u32_e32 v239, s41, v246
	v_add_u32_e32 v240, 4096, v239
	s_branch .Lscan_stw_done

; __device__ __forceinline__ unsigned pk2(float lo, float hi) { const f32x2 v = {lo, hi}; const bf16x2_t b = __builtin_convertvector(v, bf16x2_t); return __builtin_bit_cast(unsigned, b); }
; #define SCAN_GSTORE(buf, G_) do { if (wave < 4) *(u32x4*)(vst + (((buf) * 4 + wave) * 64 + lane) * 16) = G_; \
;         else if (wave == 4) *(u32x4*)(dst + (buf) * 1024 + lane * 16) = G_; } while (0)
; __device__ __forceinline__ void phase_scan(const Args& a, unsigned char* smem, int tid, int lane, int wave) {
;     ...
;                 unsigned* rb = red + (size_t)(rbuf * 8 + wave) * 1024 + lane; unsigned* rbx = red + (size_t)(rbuf * 8 + wave) * 1024 + (lane ^ 32);
; #pragma unroll
;                 for (int i = 0; i < 8; ++i) { unsigned* w_ = (i & 1) ? rbx : rb; w_[i * 64] = pk2(o0[2 * i], o0[2 * i + 1]); w_[512 + i * 64] = pk2(o1[2 * i], o1[2 * i + 1]); }
;             }
;             SCAN_GSTORE(nbuf, gcur);
;             __syncthreads();
;             if (gc < 512) {
;                 const int tp = tid >> 4, dv2 = (tid & 15) * 2, t = tp * 2, mt = t >> 5, tl = t & 31, pi = 2 * (tl >> 3) + ((tl & 3) >> 1), ln = ((tl >> 2) & 1) * 32 + dv2;
;                 const unsigned* rp = red + (size_t)rbuf * 8192 + (mt * 8 + pi) * 64 + (ln ^ ((pi & 1) << 5));
;                 float a0 = 0.f, a1 = 0.f, b0 = 0.f, b1 = 0.f;
; #pragma unroll
;                 for (int w = 0; w < 8; ++w) { const u32x2 v = *(const u32x2*)(rp + w * 1024); a0 += bflo(v.x); b0 += bfhi(v.x); a1 += bflo(v.y); b1 += bfhi(v.y); }
;                 bf16_t* op = O + (row0 + t) * 2048 + h * 512 + sl * 32 + dv2;
.Lscan_stw_done:
	v_lshlrev_b32_e32 v241, 2, v160
	v_xor_b32_e32 v242, 32, v160
	v_lshlrev_b32_e32 v242, 2, v242
	s_lshl_b32 s41, s0, 12
	s_cmp_lt_u32 s0, 4
	s_cselect_b32 s42, 0, 2048
	s_cselect_b32 s43, 2048, 0
	s_add_i32 s42, s42, s41
	s_add_i32 s43, s43, s41
	s_and_b32 s41, s0, 3
	s_lshl_b32 s41, s41, 12
	s_lshr_b32 s42, s0, 2
	s_lshl_b32 s42, s42, 11
	s_add_i32 s42, s42, s41
	v_add_u32_e32 v241, s42, v241
	v_add_u32_e32 v242, s42, v242
	s_lshl_b32 s41, s0, 11
	s_add_i32 s41, s41, 0x14000
	v_add_u32_e32 v243, s41, v234
	s_xor_b32 s41, s0, 4
	s_lshl_b32 s41, s41, 11
	s_add_i32 s41, s41, 0x14000
	v_add_u32_e32 v244, s41, v234
	v_lshrrev_b32_e32 v251, 4, v161
	v_lshlrev_b32_e32 v251, 1, v251
	v_and_b32_e32 v194, 15, v161
	v_lshlrev_b32_e32 v194, 1, v194
	v_lshlrev_b32_e32 v249, 12, v251
	v_lshl_add_u32 v249, v194, 1, v249
	s_lshl_b32 s41, s16, 10
	s_lshl_b32 s42, s18, 6
	s_add_i32 s41, s41, s42
	v_add_u32_e32 v249, s41, v249
	v_add_u32_e32 v250, 4096, v249
	v_lshrrev_b32_e32 v245, 5, v251
	v_and_b32_e32 v251, 31, v251
	v_lshrrev_b32_e32 v228, 3, v251
	v_bfe_u32 v229, v251, 1, 1
	v_lshl_add_u32 v228, v228, 1, v229
	v_lshl_add_u32 v245, v245, 3, v228
	v_bfe_u32 v230, v251, 2, 1
	v_lshl_add_u32 v230, v230, 5, v194
	v_and_b32_e32 v228, 1, v228
	v_lshlrev_b32_e32 v228, 5, v228
	v_xor_b32_e32 v230, v230, v228
	v_lshl_add_u32 v245, v245, 6, v230
	v_lshlrev_b32_e32 v245, 2, v245
	s_cmp_lt_u32 s0, 4
	s_cbranch_scc0 .Lscan_gb_ge4
	s_lshl_b32 s41, s0, 10
	v_add_u32_e32 v194, s41, v234
	v_mov_b32_e32 v195, 0
	v_lshl_add_u64 v[236:237], s[48:49], 0, v[194:195]
	v_mov_b32_e32 v238, 0x40000
	s_branch .Lscan_gb_done

; __device__ __forceinline__ void phase_scan(const Args& a, unsigned char* smem, int tid, int lane, int wave) {
;     ...
;     for (int wu = blockIdx.x; wu < 256; wu += gridDim.x) {
;         const int combo = (wu & 7) * 2 + (wu >> 7), sl = (wu >> 3) & 15;
;         const int b = combo >> 3, h = (combo >> 1) & 3, dir = combo & 1;
;         const bf16_t* QE = (const bf16_t*)(a.ws + (dir ? WS_AZ : WS_BQ));
;         const bf16_t* KDT = (const bf16_t*)(a.ws + (dir ? WS_AVT : WS_AK));
;         const bf16_t* ATT = (const bf16_t*)(a.ws + WS_ATT) + (size_t)dir * 512 * 4 * 4096;
;         const float* DL = (const float*)(a.ws + WS_DL) + (size_t)dir * 520 * 1024;
;         const bf16_t* BVF = (const bf16_t*)(a.ws + WS_BVT) + (size_t)lane * 8;
;         bf16_t* O = (bf16_t*)((unsigned char*)a.out + (dir ? DO_OB : DO_OF));
;         f32x16 S;
; #pragma unroll
;         for (int i = 0; i < 16; ++i) S[i] = 0.f;
;         bf16x8 vB[4], qeA[4], atA; f32x4 dl[4];
;         bf16x8 nqe[4], nat;
;         u32x4 gcur = {0u, 0u, 0u, 0u}, gnxt = {0u, 0u, 0u, 0u};
;     ...
;         const unsigned char* scb; unsigned scsg;
;         { const int q16s = sl * 16 + (lane & 15);
;           if (wave == 5) { if (lane < 16) { scb = (const unsigned char*)KDT + (size_t)h * 32768 + (size_t)q16s * 128; scsg = 131072u; }
;                            else if (lane < 32) { scb = (const unsigned char*)QE + (size_t)h * 512 + (size_t)(q16s >> 2) * 2048 + (q16s & 3) * 128; scsg = 131072u; }
;                            else if (lane < 36) { scb = (const unsigned char*)ATT + (size_t)h * 8192 + (size_t)(sl * 4 + lane - 32) * 128; scsg = 32768u; }
;                            else { scb = (const unsigned char*)DL + (size_t)h * 1024 + (lane & 7) * 128; scsg = 4096u; } }
;           else if (wave == 6) { scb = (const unsigned char*)(a.ws + WS_BVT) + (size_t)(h * 16 + sl) * 4096 + (size_t)(lane & 31) * 128; scsg = 262144u; }
;           else { scb = (const unsigned char*)DL + (size_t)h * 1024; scsg = 0u; } }
;         unsigned scA = 0u, scB = 0u;
;         __syncthreads();
;         SCAN_GLOAD(0, gcur); SCAN_GSTORE(0, gcur);
;         SCAN_GLOAD(1, gcur);
;         SCAN_LOAD(0, qeA, atA);
;         __syncthreads();
;         SCAN_LREAD(0, vB, dl);
;         __builtin_amdgcn_s_waitcnt(0x0F70);
.Lscan_gb_done:
	v_lshrrev_b32_e32 v251, 5, v160
	v_lshlrev_b32_e32 v251, 4, v251
	s_lshl_b32 s41, s0, 7
	v_add_u32_e32 v251, s41, v251
	s_cmp_eq_u32 s17, 1
	s_cselect_b32 s40, 3, 0
	s_lshl_b32 s41, s15, 2
	s_add_i32 s40, s40, s41
	s_addk_i32 s40, 0x200
	s_lshl_b32 s41, s40, 17
	s_add_u32 s32, s20, s41
	s_addc_u32 s33, s21, 0
	s_lshl_b32 s41, s40, 18
	s_add_u32 s34, s48, s41
	s_addc_u32 s35, s49, 0
	s_lshl_b32 s41, s40, 12
	s_add_u32 s36, s46, s41
	s_addc_u32 s37, s47, 0
	global_load_dwordx4 v[16:19], v235, s[32:33]
	global_load_dwordx4 v[20:23], v235, s[32:33] offset:1024
	global_load_dwordx4 v[24:27], v235, s[32:33] offset:2048
	global_load_dwordx4 v[28:31], v235, s[32:33] offset:3072
	global_load_dwordx4 v[80:83], v234, s[34:35]
	global_load_dwordx4 v[84:87], v234, s[34:35] offset:1024
	global_load_dwordx4 v[88:91], v234, s[34:35] offset:2048
	global_load_dwordx4 v[92:95], v234, s[34:35] offset:3072
	global_load_dwordx4 v[144:147], v251, s[36:37]
	global_load_dwordx4 v[148:151], v251, s[36:37] offset:32
	global_load_dwordx4 v[152:155], v251, s[36:37] offset:64
	global_load_dwordx4 v[156:159], v251, s[36:37] offset:96
	s_cmp_eq_u32 s17, 1
	s_cselect_b32 s40, 2, 1
	s_lshl_b32 s41, s15, 2
	s_add_i32 s40, s40, s41
	s_addk_i32 s40, 0x200
	s_lshl_b32 s41, s40, 17
	s_add_u32 s32, s20, s41
	s_addc_u32 s33, s21, 0
	s_lshl_b32 s41, s40, 18
	s_add_u32 s34, s48, s41
	s_addc_u32 s35, s49, 0
	s_lshl_b32 s41, s40, 12
	s_add_u32 s36, s46, s41
	s_addc_u32 s37, s47, 0
	global_load_dwordx4 v[32:35], v235, s[32:33]
	global_load_dwordx4 v[36:39], v235, s[32:33] offset:1024
	global_load_dwordx4 v[40:43], v235, s[32:33] offset:2048
	global_load_dwordx4 v[44:47], v235, s[32:33] offset:3072
	global_load_dwordx4 v[96:99], v234, s[34:35]
	global_load_dwordx4 v[100:103], v234, s[34:35] offset:1024
	global_load_dwordx4 v[104:107], v234, s[34:35] offset:2048
	global_load_dwordx4 v[108:111], v234, s[34:35] offset:3072
	global_load_dwordx4 v[162:165], v251, s[36:37]
	global_load_dwordx4 v[166:169], v251, s[36:37] offset:32
	global_load_dwordx4 v[170:173], v251, s[36:37] offset:64
	global_load_dwordx4 v[174:177], v251, s[36:37] offset:96
	s_cmp_eq_u32 s17, 1
	s_cselect_b32 s40, 1, 2
	s_lshl_b32 s41, s15, 2
	s_add_i32 s40, s40, s41
	s_addk_i32 s40, 0x200
	s_lshl_b32 s41, s40, 17
	s_add_u32 s32, s20, s41
	s_addc_u32 s33, s21, 0
	s_lshl_b32 s41, s40, 18
	s_add_u32 s34, s48, s41
	s_addc_u32 s35, s49, 0
	s_lshl_b32 s41, s40, 12
	s_add_u32 s36, s46, s41
	s_addc_u32 s37, s47, 0
	global_load_dwordx4 v[48:51], v235, s[32:33]
	global_load_dwordx4 v[52:55], v235, s[32:33] offset:1024
	global_load_dwordx4 v[56:59], v235, s[32:33] offset:2048
	global_load_dwordx4 v[60:63], v235, s[32:33] offset:3072
	global_load_dwordx4 v[112:115], v234, s[34:35]
	global_load_dwordx4 v[116:119], v234, s[34:35] offset:1024
	global_load_dwordx4 v[120:123], v234, s[34:35] offset:2048
	global_load_dwordx4 v[124:127], v234, s[34:35] offset:3072
	global_load_dwordx4 v[178:181], v251, s[36:37]
	global_load_dwordx4 v[182:185], v251, s[36:37] offset:32
	global_load_dwordx4 v[186:189], v251, s[36:37] offset:64
	global_load_dwordx4 v[190:193], v251, s[36:37] offset:96
	s_cmp_eq_u32 s17, 1
	s_cselect_b32 s40, 0, 3
	s_lshl_b32 s41, s15, 2
	s_add_i32 s40, s40, s41
	s_addk_i32 s40, 0x200
	s_lshl_b32 s41, s40, 17
	s_add_u32 s32, s20, s41
	s_addc_u32 s33, s21, 0
	s_lshl_b32 s41, s40, 18
	s_add_u32 s34, s48, s41
	s_addc_u32 s35, s49, 0
	s_lshl_b32 s41, s40, 12
	s_add_u32 s36, s46, s41
	s_addc_u32 s37, s47, 0
	global_load_dwordx4 v[64:67], v235, s[32:33]
	global_load_dwordx4 v[68:71], v235, s[32:33] offset:1024
	global_load_dwordx4 v[72:75], v235, s[32:33] offset:2048
	global_load_dwordx4 v[76:79], v235, s[32:33] offset:3072
	global_load_dwordx4 v[128:131], v234, s[34:35]
	global_load_dwordx4 v[132:135], v234, s[34:35] offset:1024
	global_load_dwordx4 v[136:139], v234, s[34:35] offset:2048
	global_load_dwordx4 v[140:143], v234, s[34:35] offset:3072
	global_load_dwordx4 v[194:197], v251, s[36:37]
	global_load_dwordx4 v[198:201], v251, s[36:37] offset:32
	global_load_dwordx4 v[202:205], v251, s[36:37] offset:64
	global_load_dwordx4 v[206:209], v251, s[36:37] offset:96
	s_lshl_b32 s41, s0, 10
	v_add_u32_e32 v251, s41, v234
	s_waitcnt vmcnt(36)
	v_mfma_f32_32x32x16_bf16 v[0:15], v[16:19], v[80:83], 0
	v_mfma_f32_32x32x16_bf16 v[0:15], v[20:23], v[84:87], v[0:15]
	v_mfma_f32_32x32x16_bf16 v[0:15], v[24:27], v[88:91], v[0:15]
	v_mfma_f32_32x32x16_bf16 v[0:15], v[28:31], v[92:95], v[0:15]
	s_waitcnt vmcnt(24)
	s_nop 15
	v_pk_mul_f32 v[0:1], v[162:163], v[0:1]
	v_pk_mul_f32 v[2:3], v[164:165], v[2:3]
	v_pk_mul_f32 v[4:5], v[166:167], v[4:5]
	v_pk_mul_f32 v[6:7], v[168:169], v[6:7]
	v_pk_mul_f32 v[8:9], v[170:171], v[8:9]
	v_pk_mul_f32 v[10:11], v[172:173], v[10:11]
	v_pk_mul_f32 v[12:13], v[174:175], v[12:13]
	v_pk_mul_f32 v[14:15], v[176:177], v[14:15]
	s_nop 1
	v_mfma_f32_32x32x16_bf16 v[0:15], v[32:35], v[96:99], v[0:15]
	v_mfma_f32_32x32x16_bf16 v[0:15], v[36:39], v[100:103], v[0:15]
	v_mfma_f32_32x32x16_bf16 v[0:15], v[40:43], v[104:107], v[0:15]
	v_mfma_f32_32x32x16_bf16 v[0:15], v[44:47], v[108:111], v[0:15]
	s_waitcnt vmcnt(12)
	s_nop 15
	v_pk_mul_f32 v[0:1], v[178:179], v[0:1]
	v_pk_mul_f32 v[2:3], v[180:181], v[2:3]
	v_pk_mul_f32 v[4:5], v[182:183], v[4:5]
	v_pk_mul_f32 v[6:7], v[184:185], v[6:7]
	v_pk_mul_f32 v[8:9], v[186:187], v[8:9]
	v_pk_mul_f32 v[10:11], v[188:189], v[10:11]
	v_pk_mul_f32 v[12:13], v[190:191], v[12:13]
	v_pk_mul_f32 v[14:15], v[192:193], v[14:15]
	s_nop 1
	v_mfma_f32_32x32x16_bf16 v[0:15], v[48:51], v[112:115], v[0:15]
	v_mfma_f32_32x32x16_bf16 v[0:15], v[52:55], v[116:119], v[0:15]
	v_mfma_f32_32x32x16_bf16 v[0:15], v[56:59], v[120:123], v[0:15]
	v_mfma_f32_32x32x16_bf16 v[0:15], v[60:63], v[124:127], v[0:15]
	s_waitcnt vmcnt(0)
	s_nop 15
	v_pk_mul_f32 v[0:1], v[194:195], v[0:1]
	v_pk_mul_f32 v[2:3], v[196:197], v[2:3]
	v_pk_mul_f32 v[4:5], v[198:199], v[4:5]
	v_pk_mul_f32 v[6:7], v[200:201], v[6:7]
	v_pk_mul_f32 v[8:9], v[202:203], v[8:9]
	v_pk_mul_f32 v[10:11], v[204:205], v[10:11]
	v_pk_mul_f32 v[12:13], v[206:207], v[12:13]
	v_pk_mul_f32 v[14:15], v[208:209], v[14:15]
	s_nop 1
	v_mfma_f32_32x32x16_bf16 v[0:15], v[64:67], v[128:131], v[0:15]
	v_mfma_f32_32x32x16_bf16 v[0:15], v[68:71], v[132:135], v[0:15]
	v_mfma_f32_32x32x16_bf16 v[0:15], v[72:75], v[136:139], v[0:15]
	v_mfma_f32_32x32x16_bf16 v[0:15], v[76:79], v[140:143], v[0:15]
	s_nop 15
	s_nop 3
	s_mov_b32 s30, 0
	s_mov_b32 s42, 0
	s_min_u32 s42, s42, 0xff
	s_mul_i32 s42, s42, s29
	s_add_i32 s42, s42, s28
	v_mad_u64_u32 v[194:195], s[44:45], v238, s42, v[236:237]
	global_load_dwordx4 v[204:207], v[194:195], off
	s_mov_b32 s42, 1
	s_min_u32 s42, s42, 0xff
	s_mul_i32 s42, s42, s29
	s_add_i32 s42, s42, s28
	v_mad_u64_u32 v[194:195], s[44:45], v238, s42, v[236:237]
	global_load_dwordx4 v[208:211], v[194:195], off
	s_waitcnt vmcnt(0)
	s_barrier
; __device__ __forceinline__ void phase_scan(const Args& a, unsigned char* smem, int tid, int lane, int wave) {
;     ...
;         __syncthreads();
;         SCAN_GLOAD(0, gcur); SCAN_GSTORE(0, gcur);
;         SCAN_GLOAD(1, gcur);
;         SCAN_LOAD(0, qeA, atA);
;         __syncthreads();
;         SCAN_LREAD(0, vB, dl);
;         __builtin_amdgcn_s_waitcnt(0x0F70);
;         auto stepf = [&](const int step, unsigned& sc_issue, unsigned& sc_consume) __attribute__((always_inline)) {
;             const int nstep = step < 259 ? step + 1 : step, n2 = step < 258 ? step + 2 : 259;
;             SCAN_LOAD(nstep, nqe, nat);
;             SCAN_GLOAD(n2, gnxt);
;     ...
;             { int ss = step + SCOUT; ss = ss > 259 ? 259 : ss; const int gcs = SCAN_GC(ss); sc_issue = *(const unsigned*)(scb + (size_t)gcs * scsg); }
;     ...
;             const int gc = SCAN_GC(step); const size_t row0 = (size_t)gc * 64;
;             bf16x8 kdA[4];
;             { const bf16_t* kp = KDT + (((size_t)gc * 4 + h) * 8 + kb) * 2048 + lane * 8;
; #pragma unroll
;               for (int q = 0; q < 4; ++q) kdA[q] = *(const bf16x8*)(kp + 512 * q); }
;             const int rbuf = step & 1, nbuf = rbuf ^ 1;
;             if (gc < 512) {
;                 u32x4 s0, s1;
;                 s0.x = pk2(S[0], S[1]); s0.y = pk2(S[2], S[3]); s0.z = pk2(S[4], S[5]); s0.w = pk2(S[6], S[7]);
;                 s1.x = pk2(S[8], S[9]); s1.y = pk2(S[10], S[11]); s1.z = pk2(S[12], S[13]); s1.w = pk2(S[14], S[15]);
;                 const bf16x8 sb0 = __builtin_bit_cast(bf16x8, s0), sb1 = __builtin_bit_cast(bf16x8, s1);
;                 f32x16 o0, o1;
; #pragma unroll
;                 for (int i = 0; i < 16; ++i) { o0[i] = 0.f; o1[i] = 0.f; }
;                 o0 = mfma32(qeA[0], sb0, o0); o0 = mfma32(qeA[1], sb1, o0);
;                 o1 = mfma32(qeA[2], sb0, o1); o1 = mfma32(qeA[3], sb1, o1);
;                 const int w3 = wave & 3;
;                 const bf16x8 vs = w3 == 0 ? vB[0] : (w3 == 1 ? vB[1] : (w3 == 2 ? vB[2] : vB[3]));
;                 if (wave < 4) o0 = mfma32(atA, vs, o0); else o1 = mfma32(atA, vs, o1);
;                 unsigned* rb = red + (size_t)(rbuf * 8 + wave) * 1024 + lane; unsigned* rbx = red + (size_t)(rbuf * 8 + wave) * 1024 + (lane ^ 32);
; #pragma unroll
	ds_write_b128 v239, v[204:207]
	ds_write_b128 v240, v[208:211]
	v_cvt_pk_bf16_f32 v48, v0, v1
	v_cvt_pk_bf16_f32 v49, v2, v3
	v_cvt_pk_bf16_f32 v50, v4, v5
	v_cvt_pk_bf16_f32 v51, v6, v7
	v_cvt_pk_bf16_f32 v52, v8, v9
	v_cvt_pk_bf16_f32 v53, v10, v11
	v_cvt_pk_bf16_f32 v54, v12, v13
	v_cvt_pk_bf16_f32 v55, v14, v15
	ds_write_b128 v243, v[48:51] offset:0
	ds_write_b128 v243, v[52:55] offset:1024
	s_waitcnt lgkmcnt(0)
	s_barrier
	ds_read_b128 v[128:131], v246 offset:0
	ds_read_b128 v[132:135], v246 offset:1024
	ds_read_b128 v[136:139], v246 offset:2048
	ds_read_b128 v[140:143], v246 offset:3072
	ds_read_b128 v[196:199], v248 offset:0
	ds_read_b128 v[162:165], v247 offset:0
	ds_read_b128 v[166:169], v247 offset:32
	ds_read_b128 v[170:173], v247 offset:64
	ds_read_b128 v[174:177], v247 offset:96
	s_lshl_b32 s53, s29, 17
	s_lshl_b32 s54, s29, 15
	s_lshl_b32 s55, s29, 18
	s_ashr_i32 s56, s29, 31
	s_mov_b32 s40, 0
	s_mul_i32 s40, s40, s29
	s_add_i32 s40, s40, s28
	s_lshl_b32 s41, s40, 17
	s_add_u32 s32, s20, s41
	s_addc_u32 s33, s21, 0
	s_add_u32 s34, s22, s41
	s_addc_u32 s35, s23, 0
	s_lshl_b32 s41, s40, 15
	s_add_u32 s36, s24, s41
	s_addc_u32 s37, s25, 0
	s_add_i32 s42, s31, -2
	s_mul_i32 s42, s42, s29
	s_add_i32 s42, s42, s28
	v_mad_u64_u32 v[194:195], s[44:45], v238, s42, v[236:237]
	v_mul_lo_u32 v254, v238, s29
	v_ashrrev_i32_e32 v255, 31, v254
	s_lshl_b32 s40, s28, 18
	s_add_u32 s38, s26, s40
	s_addc_u32 s39, s27, 0
	global_load_dwordx4 v[204:207], v[194:195], off
	v_lshl_add_u64 v[194:195], v[194:195], 0, v[254:255]
	global_load_dwordx4 v[76:79], v235, s[32:33]
	global_load_dwordx4 v[80:83], v235, s[32:33] offset:1024
	global_load_dwordx4 v[84:87], v235, s[32:33] offset:2048
	global_load_dwordx4 v[88:91], v235, s[32:33] offset:3072
	global_load_dwordx4 v[56:59], v232, s[34:35] offset:-4096
	global_load_dwordx4 v[60:63], v232, s[34:35]
	global_load_dwordx4 v[64:67], v233, s[34:35] offset:-4096
	global_load_dwordx4 v[68:71], v233, s[34:35]
	global_load_dwordx4 v[72:75], v251, s[36:37]
	s_add_u32 s32, s32, s53
	s_addc_u32 s33, s33, s56
	s_add_u32 s34, s34, s53
	s_addc_u32 s35, s35, s56
	s_add_u32 s36, s36, s54
	s_addc_u32 s37, s37, s56
	global_load_dwordx4 v[208:211], v[194:195], off
	v_lshl_add_u64 v[194:195], v[194:195], 0, v[254:255]
	global_load_dwordx4 v[112:115], v235, s[32:33]
	global_load_dwordx4 v[116:119], v235, s[32:33] offset:1024
	global_load_dwordx4 v[120:123], v235, s[32:33] offset:2048
	global_load_dwordx4 v[124:127], v235, s[32:33] offset:3072
	global_load_dwordx4 v[92:95], v232, s[34:35] offset:-4096
	global_load_dwordx4 v[96:99], v232, s[34:35]
	global_load_dwordx4 v[100:103], v233, s[34:35] offset:-4096
	global_load_dwordx4 v[104:107], v233, s[34:35]
	global_load_dwordx4 v[108:111], v251, s[36:37]
	s_add_u32 s32, s32, s53
	s_addc_u32 s33, s33, s56
	s_add_u32 s34, s34, s53
	s_addc_u32 s35, s35, s56
	s_add_u32 s36, s36, s54
	s_addc_u32 s37, s37, s56
	s_waitcnt lgkmcnt(0)
	s_barrier
	s_cmp_lt_u32 s0, 4
	s_cbranch_scc0 .Lscan_pathB
	s_waitcnt vmcnt(10)
	ds_write_b128 v239, v[204:207]
	global_load_dwordx4 v[204:207], v[194:195], off
	v_lshl_add_u64 v[194:195], v[194:195], 0, v[254:255]
	ds_read_b128 v[32:35], v244 offset:0
	ds_read_b128 v[36:39], v244 offset:1024
	v_mfma_f32_32x32x16_bf16 v[16:31], v[56:59], v[48:51], 0
	v_pk_mul_f32 v[0:1], v[162:163], v[0:1]
	v_pk_mul_f32 v[2:3], v[164:165], v[2:3]
	v_pk_mul_f32 v[4:5], v[166:167], v[4:5]
	v_pk_mul_f32 v[6:7], v[168:169], v[6:7]
	v_mfma_f32_32x32x16_bf16 v[16:31], v[60:63], v[52:55], v[16:31]
	v_pk_mul_f32 v[8:9], v[170:171], v[8:9]
	v_pk_mul_f32 v[10:11], v[172:173], v[10:11]
	v_pk_mul_f32 v[12:13], v[174:175], v[12:13]
	v_pk_mul_f32 v[14:15], v[176:177], v[14:15]
	s_waitcnt lgkmcnt(0)
	v_mfma_f32_32x32x16_bf16 v[16:31], v[64:67], v[32:35], v[16:31]
	v_mfma_f32_32x32x16_bf16 v[16:31], v[68:71], v[36:39], v[16:31]
	v_mfma_f32_32x32x16_bf16 v[16:31], v[72:75], v[196:199], v[16:31]
	v_mfma_f32_32x32x16_bf16 v[0:15], v[76:79], v[128:131], v[0:15]
	v_mfma_f32_32x32x16_bf16 v[0:15], v[80:83], v[132:135], v[0:15]
	v_mfma_f32_32x32x16_bf16 v[0:15], v[84:87], v[136:139], v[0:15]
	v_mfma_f32_32x32x16_bf16 v[0:15], v[88:91], v[140:143], v[0:15]
	ds_read_b128 v[144:147], v246 offset:4096
	global_load_dwordx4 v[76:79], v235, s[32:33]
	ds_read_b128 v[148:151], v246 offset:5120
	ds_read_b128 v[152:155], v246 offset:6144
	global_load_dwordx4 v[80:83], v235, s[32:33] offset:1024
	ds_read_b128 v[156:159], v246 offset:7168
	ds_read_b128 v[200:203], v248 offset:4096
	global_load_dwordx4 v[84:87], v235, s[32:33] offset:2048
	ds_read_b128 v[178:181], v247 offset:1024
	ds_read_b128 v[182:185], v247 offset:1056
	ds_read_b128 v[186:189], v247 offset:1088
	global_load_dwordx4 v[88:91], v235, s[32:33] offset:3072
	ds_read_b128 v[190:193], v247 offset:1120
	v_cvt_pk_bf16_f32 v16, v16, v17
	global_load_dwordx4 v[56:59], v232, s[34:35] offset:-4096
	v_cvt_pk_bf16_f32 v18, v18, v19
	v_cvt_pk_bf16_f32 v20, v20, v21
	global_load_dwordx4 v[60:63], v232, s[34:35]
	v_cvt_pk_bf16_f32 v22, v22, v23
	v_cvt_pk_bf16_f32 v24, v24, v25
	v_cvt_pk_bf16_f32 v26, v26, v27
	global_load_dwordx4 v[64:67], v233, s[34:35] offset:-4096
	v_cvt_pk_bf16_f32 v28, v28, v29
	v_cvt_pk_bf16_f32 v30, v30, v31
	global_load_dwordx4 v[68:71], v233, s[34:35]
	ds_write2st64_b32 v241, v16, v20 offset0:0 offset1:2
	ds_write2st64_b32 v242, v18, v22 offset0:1 offset1:3
	global_load_dwordx4 v[72:75], v251, s[36:37]
	ds_write2st64_b32 v241, v24, v28 offset0:4 offset1:6
	ds_write2st64_b32 v242, v26, v30 offset0:5 offset1:7
	s_add_u32 s32, s32, s53
	s_addc_u32 s33, s33, s56
	s_add_u32 s34, s34, s53
	s_addc_u32 s35, s35, s56
	s_add_u32 s36, s36, s54
	s_addc_u32 s37, s37, s56
	v_cvt_pk_bf16_f32 v48, v0, v1
	v_cvt_pk_bf16_f32 v49, v2, v3
	v_cvt_pk_bf16_f32 v50, v4, v5
	v_cvt_pk_bf16_f32 v51, v6, v7
	v_cvt_pk_bf16_f32 v52, v8, v9
	v_cvt_pk_bf16_f32 v53, v10, v11
	v_cvt_pk_bf16_f32 v54, v12, v13
	v_cvt_pk_bf16_f32 v55, v14, v15
	ds_write_b128 v243, v[48:51] offset:16384
	ds_write_b128 v243, v[52:55] offset:17408
	s_waitcnt lgkmcnt(0)
	s_barrier
; __device__ __forceinline__ void phase_scan(const Args& a, unsigned char* smem, int tid, int lane, int wave) {
;     ...
;             if (gc < 512) {
;                 u32x4 s0, s1;
;                 s0.x = pk2(S[0], S[1]); s0.y = pk2(S[2], S[3]); s0.z = pk2(S[4], S[5]); s0.w = pk2(S[6], S[7]);
;                 s1.x = pk2(S[8], S[9]); s1.y = pk2(S[10], S[11]); s1.z = pk2(S[12], S[13]); s1.w = pk2(S[14], S[15]);
;                 const bf16x8 sb0 = __builtin_bit_cast(bf16x8, s0), sb1 = __builtin_bit_cast(bf16x8, s1);
;                 f32x16 o0, o1;
; #pragma unroll
;                 for (int i = 0; i < 16; ++i) { o0[i] = 0.f; o1[i] = 0.f; }
;                 o0 = mfma32(qeA[0], sb0, o0); o0 = mfma32(qeA[1], sb1, o0);
;                 o1 = mfma32(qeA[2], sb0, o1); o1 = mfma32(qeA[3], sb1, o1);
;                 const int w3 = wave & 3;
;                 const bf16x8 vs = w3 == 0 ? vB[0] : (w3 == 1 ? vB[1] : (w3 == 2 ? vB[2] : vB[3]));
;                 if (wave < 4) o0 = mfma32(atA, vs, o0); else o1 = mfma32(atA, vs, o1);
;                 unsigned* rb = red + (size_t)(rbuf * 8 + wave) * 1024 + lane; unsigned* rbx = red + (size_t)(rbuf * 8 + wave) * 1024 + (lane ^ 32);
; #pragma unroll
;                 for (int i = 0; i < 8; ++i) { unsigned* w_ = (i & 1) ? rbx : rb; w_[i * 64] = pk2(o0[2 * i], o0[2 * i + 1]); w_[512 + i * 64] = pk2(o1[2 * i], o1[2 * i + 1]); }
;             }
;             SCAN_GSTORE(nbuf, gcur);
;             __syncthreads();
;             if (gc < 512) {
;                 const int tp = tid >> 4, dv2 = (tid & 15) * 2, t = tp * 2, mt = t >> 5, tl = t & 31, pi = 2 * (tl >> 3) + ((tl & 3) >> 1), ln = ((tl >> 2) & 1) * 32 + dv2;
;                 const unsigned* rp = red + (size_t)rbuf * 8192 + (mt * 8 + pi) * 64 + (ln ^ ((pi & 1) << 5));
;                 float a0 = 0.f, a1 = 0.f, b0 = 0.f, b1 = 0.f;
; #pragma unroll
;                 for (int w = 0; w < 8; ++w) { const u32x2 v = *(const u32x2*)(rp + w * 1024); a0 += bflo(v.x); b0 += bfhi(v.x); a1 += bflo(v.y); b1 += bfhi(v.y); }
;                 bf16_t* op = O + (row0 + t) * 2048 + h * 512 + sl * 32 + dv2;
;                 *(unsigned*)op = pk2(a0, a1); *(unsigned*)(op + 2048) = pk2(b0, b1);
;             }
;             f32x4 ndl[4]; bf16x8 nvB[4];
;             SCAN_LREAD(nbuf, nvB, ndl);
; #pragma unroll
;             for (int i = 0; i < 16; ++i) S[i] *= dl[i >> 2][i & 3];
; #pragma unroll
	s_waitcnt vmcnt(10)
	ds_write_b128 v240, v[208:211]
	global_load_dwordx4 v[208:211], v[194:195], off
	v_lshl_add_u64 v[194:195], v[194:195], 0, v[254:255]
	ds_read_b128 v[32:35], v244 offset:16384
	ds_read_b128 v[36:39], v244 offset:17408
	v_mfma_f32_32x32x16_bf16 v[16:31], v[92:95], v[48:51], 0
	v_pk_mul_f32 v[0:1], v[178:179], v[0:1]
	v_pk_mul_f32 v[2:3], v[180:181], v[2:3]
	v_pk_mul_f32 v[4:5], v[182:183], v[4:5]
	v_pk_mul_f32 v[6:7], v[184:185], v[6:7]
	v_mfma_f32_32x32x16_bf16 v[16:31], v[96:99], v[52:55], v[16:31]
	v_pk_mul_f32 v[8:9], v[186:187], v[8:9]
	v_pk_mul_f32 v[10:11], v[188:189], v[10:11]
	v_pk_mul_f32 v[12:13], v[190:191], v[12:13]
	v_pk_mul_f32 v[14:15], v[192:193], v[14:15]
	s_waitcnt lgkmcnt(0)
	v_mfma_f32_32x32x16_bf16 v[16:31], v[100:103], v[32:35], v[16:31]
	v_mfma_f32_32x32x16_bf16 v[16:31], v[104:107], v[36:39], v[16:31]
	v_mfma_f32_32x32x16_bf16 v[16:31], v[108:111], v[200:203], v[16:31]
	v_mfma_f32_32x32x16_bf16 v[0:15], v[112:115], v[144:147], v[0:15]
	v_mfma_f32_32x32x16_bf16 v[0:15], v[116:119], v[148:151], v[0:15]
	v_mfma_f32_32x32x16_bf16 v[0:15], v[120:123], v[152:155], v[0:15]
	v_mfma_f32_32x32x16_bf16 v[0:15], v[124:127], v[156:159], v[0:15]
	ds_read2st64_b64 v[212:215], v245 offset0:0 offset1:8
	ds_read2st64_b64 v[216:219], v245 offset0:16 offset1:24
	ds_read_b128 v[128:131], v246 offset:0
	global_load_dwordx4 v[112:115], v235, s[32:33]
	ds_read_b128 v[132:135], v246 offset:1024
	ds_read_b128 v[136:139], v246 offset:2048
	ds_read_b128 v[140:143], v246 offset:3072
	ds_read_b128 v[196:199], v248 offset:0
	ds_read_b128 v[162:165], v247 offset:0
	ds_read_b128 v[166:169], v247 offset:32
	global_load_dwordx4 v[116:119], v235, s[32:33] offset:1024
	ds_read_b128 v[170:173], v247 offset:64
	ds_read_b128 v[174:177], v247 offset:96
	s_waitcnt lgkmcnt(10)
	v_lshlrev_b32_e32 v229, 16, v213
	v_lshlrev_b32_e32 v228, 16, v212
	v_pk_add_f32 v[228:229], v[228:229], 0 op_sel_hi:[1,0]
	global_load_dwordx4 v[120:123], v235, s[32:33] offset:2048
	v_and_b32_e32 v231, 0xffff0000, v213
	v_and_b32_e32 v230, 0xffff0000, v212
	v_pk_add_f32 v[230:231], v[230:231], 0 op_sel_hi:[1,0]
	v_lshlrev_b32_e32 v41, 16, v215
	v_lshlrev_b32_e32 v40, 16, v214
	v_pk_add_f32 v[228:229], v[228:229], v[40:41]
	global_load_dwordx4 v[124:127], v235, s[32:33] offset:3072
	v_and_b32_e32 v215, 0xffff0000, v215
	v_and_b32_e32 v214, 0xffff0000, v214
	v_pk_add_f32 v[230:231], v[230:231], v[214:215]
	s_waitcnt lgkmcnt(9)
	v_lshlrev_b32_e32 v41, 16, v217
	v_lshlrev_b32_e32 v40, 16, v216
	global_load_dwordx4 v[92:95], v232, s[34:35] offset:-4096
	v_pk_add_f32 v[228:229], v[228:229], v[40:41]
	v_and_b32_e32 v217, 0xffff0000, v217
	v_and_b32_e32 v216, 0xffff0000, v216
	v_pk_add_f32 v[230:231], v[230:231], v[216:217]
	v_lshlrev_b32_e32 v41, 16, v219
	v_lshlrev_b32_e32 v40, 16, v218
	global_load_dwordx4 v[96:99], v232, s[34:35]
	v_pk_add_f32 v[228:229], v[228:229], v[40:41]
	v_and_b32_e32 v219, 0xffff0000, v219
	v_and_b32_e32 v218, 0xffff0000, v218
	v_pk_add_f32 v[230:231], v[230:231], v[218:219]
	v_cvt_pk_bf16_f32 v228, v228, v229
	v_cvt_pk_bf16_f32 v230, v230, v231
	global_load_dwordx4 v[100:103], v233, s[34:35] offset:-4096
	global_store_dword v249, v228, s[38:39]
	global_store_dword v250, v230, s[38:39]
	s_add_u32 s38, s38, s55
	s_addc_u32 s39, s39, s56
	v_cvt_pk_bf16_f32 v16, v16, v17
	v_cvt_pk_bf16_f32 v18, v18, v19
	global_load_dwordx4 v[104:107], v233, s[34:35]
	v_cvt_pk_bf16_f32 v20, v20, v21
	v_cvt_pk_bf16_f32 v22, v22, v23
	v_cvt_pk_bf16_f32 v24, v24, v25
	v_cvt_pk_bf16_f32 v26, v26, v27
	v_cvt_pk_bf16_f32 v28, v28, v29
	v_cvt_pk_bf16_f32 v30, v30, v31
	global_load_dwordx4 v[108:111], v251, s[36:37]
	ds_write2st64_b32 v241, v16, v20 offset0:64 offset1:66
	ds_write2st64_b32 v242, v18, v22 offset0:65 offset1:67
	ds_write2st64_b32 v241, v24, v28 offset0:68 offset1:70
	ds_write2st64_b32 v242, v26, v30 offset0:69 offset1:71
	s_add_u32 s32, s32, s53
	s_addc_u32 s33, s33, s56
	s_add_u32 s34, s34, s53
	s_addc_u32 s35, s35, s56
	s_add_u32 s36, s36, s54
	s_addc_u32 s37, s37, s56
	v_cvt_pk_bf16_f32 v48, v0, v1
	v_cvt_pk_bf16_f32 v49, v2, v3
	v_cvt_pk_bf16_f32 v50, v4, v5
	v_cvt_pk_bf16_f32 v51, v6, v7
	v_cvt_pk_bf16_f32 v52, v8, v9
	v_cvt_pk_bf16_f32 v53, v10, v11
	v_cvt_pk_bf16_f32 v54, v12, v13
	v_cvt_pk_bf16_f32 v55, v14, v15
	ds_write_b128 v243, v[48:51] offset:0
	ds_write_b128 v243, v[52:55] offset:1024
	s_waitcnt lgkmcnt(0)
	s_barrier
; __device__ __forceinline__ void phase_scan(const Args& a, unsigned char* smem, int tid, int lane, int wave) {
;     ...
;             if (gc < 512) {
;                 u32x4 s0, s1;
;                 s0.x = pk2(S[0], S[1]); s0.y = pk2(S[2], S[3]); s0.z = pk2(S[4], S[5]); s0.w = pk2(S[6], S[7]);
;                 s1.x = pk2(S[8], S[9]); s1.y = pk2(S[10], S[11]); s1.z = pk2(S[12], S[13]); s1.w = pk2(S[14], S[15]);
;                 const bf16x8 sb0 = __builtin_bit_cast(bf16x8, s0), sb1 = __builtin_bit_cast(bf16x8, s1);
;                 f32x16 o0, o1;
; #pragma unroll
;                 for (int i = 0; i < 16; ++i) { o0[i] = 0.f; o1[i] = 0.f; }
;                 o0 = mfma32(qeA[0], sb0, o0); o0 = mfma32(qeA[1], sb1, o0);
;                 o1 = mfma32(qeA[2], sb0, o1); o1 = mfma32(qeA[3], sb1, o1);
;                 const int w3 = wave & 3;
;                 const bf16x8 vs = w3 == 0 ? vB[0] : (w3 == 1 ? vB[1] : (w3 == 2 ? vB[2] : vB[3]));
;                 if (wave < 4) o0 = mfma32(atA, vs, o0); else o1 = mfma32(atA, vs, o1);
;                 unsigned* rb = red + (size_t)(rbuf * 8 + wave) * 1024 + lane; unsigned* rbx = red + (size_t)(rbuf * 8 + wave) * 1024 + (lane ^ 32);
; #pragma unroll
;                 for (int i = 0; i < 8; ++i) { unsigned* w_ = (i & 1) ? rbx : rb; w_[i * 64] = pk2(o0[2 * i], o0[2 * i + 1]); w_[512 + i * 64] = pk2(o1[2 * i], o1[2 * i + 1]); }
;             }
;             SCAN_GSTORE(nbuf, gcur);
;             __syncthreads();
;             if (gc < 512) {
;                 const int tp = tid >> 4, dv2 = (tid & 15) * 2, t = tp * 2, mt = t >> 5, tl = t & 31, pi = 2 * (tl >> 3) + ((tl & 3) >> 1), ln = ((tl >> 2) & 1) * 32 + dv2;
;                 const unsigned* rp = red + (size_t)rbuf * 8192 + (mt * 8 + pi) * 64 + (ln ^ ((pi & 1) << 5));
;                 float a0 = 0.f, a1 = 0.f, b0 = 0.f, b1 = 0.f;
; #pragma unroll
;                 for (int w = 0; w < 8; ++w) { const u32x2 v = *(const u32x2*)(rp + w * 1024); a0 += bflo(v.x); b0 += bfhi(v.x); a1 += bflo(v.y); b1 += bfhi(v.y); }
;                 bf16_t* op = O + (row0 + t) * 2048 + h * 512 + sl * 32 + dv2;
;                 *(unsigned*)op = pk2(a0, a1); *(unsigned*)(op + 2048) = pk2(b0, b1);
;             }
;             f32x4 ndl[4]; bf16x8 nvB[4];
;             SCAN_LREAD(nbuf, nvB, ndl);
; #pragma unroll
;             for (int i = 0; i < 16; ++i) S[i] *= dl[i >> 2][i & 3];
; #pragma unroll
	s_waitcnt vmcnt(12)
	ds_write_b128 v239, v[204:207]
	global_load_dwordx4 v[204:207], v[194:195], off
	v_lshl_add_u64 v[194:195], v[194:195], 0, v[254:255]
	ds_read_b128 v[32:35], v244 offset:0
	ds_read_b128 v[36:39], v244 offset:1024
	v_mfma_f32_32x32x16_bf16 v[16:31], v[56:59], v[48:51], 0
	v_pk_mul_f32 v[0:1], v[162:163], v[0:1]
	v_pk_mul_f32 v[2:3], v[164:165], v[2:3]
	v_pk_mul_f32 v[4:5], v[166:167], v[4:5]
	v_pk_mul_f32 v[6:7], v[168:169], v[6:7]
	v_mfma_f32_32x32x16_bf16 v[16:31], v[60:63], v[52:55], v[16:31]
	v_pk_mul_f32 v[8:9], v[170:171], v[8:9]
	v_pk_mul_f32 v[10:11], v[172:173], v[10:11]
	v_pk_mul_f32 v[12:13], v[174:175], v[12:13]
	v_pk_mul_f32 v[14:15], v[176:177], v[14:15]
	s_waitcnt lgkmcnt(0)
	v_mfma_f32_32x32x16_bf16 v[16:31], v[64:67], v[32:35], v[16:31]
	v_mfma_f32_32x32x16_bf16 v[16:31], v[68:71], v[36:39], v[16:31]
	v_mfma_f32_32x32x16_bf16 v[16:31], v[72:75], v[196:199], v[16:31]
	v_mfma_f32_32x32x16_bf16 v[0:15], v[76:79], v[128:131], v[0:15]
	v_mfma_f32_32x32x16_bf16 v[0:15], v[80:83], v[132:135], v[0:15]
	v_mfma_f32_32x32x16_bf16 v[0:15], v[84:87], v[136:139], v[0:15]
	v_mfma_f32_32x32x16_bf16 v[0:15], v[88:91], v[140:143], v[0:15]
	ds_read2st64_b64 v[212:215], v245 offset0:32 offset1:40
	ds_read2st64_b64 v[216:219], v245 offset0:48 offset1:56
	ds_read_b128 v[144:147], v246 offset:4096
	global_load_dwordx4 v[76:79], v235, s[32:33]
	ds_read_b128 v[148:151], v246 offset:5120
	ds_read_b128 v[152:155], v246 offset:6144
	ds_read_b128 v[156:159], v246 offset:7168
	ds_read_b128 v[200:203], v248 offset:4096
	ds_read_b128 v[178:181], v247 offset:1024
	ds_read_b128 v[182:185], v247 offset:1056
	global_load_dwordx4 v[80:83], v235, s[32:33] offset:1024
	ds_read_b128 v[186:189], v247 offset:1088
	ds_read_b128 v[190:193], v247 offset:1120
	s_waitcnt lgkmcnt(10)
	v_lshlrev_b32_e32 v229, 16, v213
	v_lshlrev_b32_e32 v228, 16, v212
	v_pk_add_f32 v[228:229], v[228:229], 0 op_sel_hi:[1,0]
	global_load_dwordx4 v[84:87], v235, s[32:33] offset:2048
	v_and_b32_e32 v231, 0xffff0000, v213
	v_and_b32_e32 v230, 0xffff0000, v212
	v_pk_add_f32 v[230:231], v[230:231], 0 op_sel_hi:[1,0]
	v_lshlrev_b32_e32 v41, 16, v215
	v_lshlrev_b32_e32 v40, 16, v214
	v_pk_add_f32 v[228:229], v[228:229], v[40:41]
	global_load_dwordx4 v[88:91], v235, s[32:33] offset:3072
	v_and_b32_e32 v215, 0xffff0000, v215
	v_and_b32_e32 v214, 0xffff0000, v214
	v_pk_add_f32 v[230:231], v[230:231], v[214:215]
	s_waitcnt lgkmcnt(9)
	v_lshlrev_b32_e32 v41, 16, v217
	v_lshlrev_b32_e32 v40, 16, v216
	global_load_dwordx4 v[56:59], v232, s[34:35] offset:-4096
	v_pk_add_f32 v[228:229], v[228:229], v[40:41]
	v_and_b32_e32 v217, 0xffff0000, v217
	v_and_b32_e32 v216, 0xffff0000, v216
	v_pk_add_f32 v[230:231], v[230:231], v[216:217]
	v_lshlrev_b32_e32 v41, 16, v219
	v_lshlrev_b32_e32 v40, 16, v218
	global_load_dwordx4 v[60:63], v232, s[34:35]
	v_pk_add_f32 v[228:229], v[228:229], v[40:41]
	v_and_b32_e32 v219, 0xffff0000, v219
	v_and_b32_e32 v218, 0xffff0000, v218
	v_pk_add_f32 v[230:231], v[230:231], v[218:219]
	v_cvt_pk_bf16_f32 v228, v228, v229
	v_cvt_pk_bf16_f32 v230, v230, v231
	global_load_dwordx4 v[64:67], v233, s[34:35] offset:-4096
	global_store_dword v249, v228, s[38:39]
	global_store_dword v250, v230, s[38:39]
	s_add_u32 s38, s38, s55
	s_addc_u32 s39, s39, s56
	v_cvt_pk_bf16_f32 v16, v16, v17
	v_cvt_pk_bf16_f32 v18, v18, v19
	global_load_dwordx4 v[68:71], v233, s[34:35]
	v_cvt_pk_bf16_f32 v20, v20, v21
	v_cvt_pk_bf16_f32 v22, v22, v23
	v_cvt_pk_bf16_f32 v24, v24, v25
	v_cvt_pk_bf16_f32 v26, v26, v27
	v_cvt_pk_bf16_f32 v28, v28, v29
	v_cvt_pk_bf16_f32 v30, v30, v31
	global_load_dwordx4 v[72:75], v251, s[36:37]
	ds_write2st64_b32 v241, v16, v20 offset0:0 offset1:2
	ds_write2st64_b32 v242, v18, v22 offset0:1 offset1:3
	ds_write2st64_b32 v241, v24, v28 offset0:4 offset1:6
	ds_write2st64_b32 v242, v26, v30 offset0:5 offset1:7
	s_add_u32 s32, s32, s53
	s_addc_u32 s33, s33, s56
	s_add_u32 s34, s34, s53
	s_addc_u32 s35, s35, s56
	s_add_u32 s36, s36, s54
	s_addc_u32 s37, s37, s56
	v_cvt_pk_bf16_f32 v48, v0, v1
	v_cvt_pk_bf16_f32 v49, v2, v3
	v_cvt_pk_bf16_f32 v50, v4, v5
	v_cvt_pk_bf16_f32 v51, v6, v7
	v_cvt_pk_bf16_f32 v52, v8, v9
	v_cvt_pk_bf16_f32 v53, v10, v11
	v_cvt_pk_bf16_f32 v54, v12, v13
	v_cvt_pk_bf16_f32 v55, v14, v15
	ds_write_b128 v243, v[48:51] offset:16384
	ds_write_b128 v243, v[52:55] offset:17408
	s_waitcnt lgkmcnt(0)
	s_barrier
; __device__ __forceinline__ void phase_scan(const Args& a, unsigned char* smem, int tid, int lane, int wave) {
;     ...
;             if (gc < 512) {
;                 u32x4 s0, s1;
;                 s0.x = pk2(S[0], S[1]); s0.y = pk2(S[2], S[3]); s0.z = pk2(S[4], S[5]); s0.w = pk2(S[6], S[7]);
;                 s1.x = pk2(S[8], S[9]); s1.y = pk2(S[10], S[11]); s1.z = pk2(S[12], S[13]); s1.w = pk2(S[14], S[15]);
;                 const bf16x8 sb0 = __builtin_bit_cast(bf16x8, s0), sb1 = __builtin_bit_cast(bf16x8, s1);
;                 f32x16 o0, o1;
; #pragma unroll
;                 for (int i = 0; i < 16; ++i) { o0[i] = 0.f; o1[i] = 0.f; }
;                 o0 = mfma32(qeA[0], sb0, o0); o0 = mfma32(qeA[1], sb1, o0);
;                 o1 = mfma32(qeA[2], sb0, o1); o1 = mfma32(qeA[3], sb1, o1);
;                 const int w3 = wave & 3;
;                 const bf16x8 vs = w3 == 0 ? vB[0] : (w3 == 1 ? vB[1] : (w3 == 2 ? vB[2] : vB[3]));
;                 if (wave < 4) o0 = mfma32(atA, vs, o0); else o1 = mfma32(atA, vs, o1);
;                 unsigned* rb = red + (size_t)(rbuf * 8 + wave) * 1024 + lane; unsigned* rbx = red + (size_t)(rbuf * 8 + wave) * 1024 + (lane ^ 32);
; #pragma unroll
;                 for (int i = 0; i < 8; ++i) { unsigned* w_ = (i & 1) ? rbx : rb; w_[i * 64] = pk2(o0[2 * i], o0[2 * i + 1]); w_[512 + i * 64] = pk2(o1[2 * i], o1[2 * i + 1]); }
;             }
;             SCAN_GSTORE(nbuf, gcur);
;             __syncthreads();
;             if (gc < 512) {
;                 const int tp = tid >> 4, dv2 = (tid & 15) * 2, t = tp * 2, mt = t >> 5, tl = t & 31, pi = 2 * (tl >> 3) + ((tl & 3) >> 1), ln = ((tl >> 2) & 1) * 32 + dv2;
;                 const unsigned* rp = red + (size_t)rbuf * 8192 + (mt * 8 + pi) * 64 + (ln ^ ((pi & 1) << 5));
;                 float a0 = 0.f, a1 = 0.f, b0 = 0.f, b1 = 0.f;
; #pragma unroll
;                 for (int w = 0; w < 8; ++w) { const u32x2 v = *(const u32x2*)(rp + w * 1024); a0 += bflo(v.x); b0 += bfhi(v.x); a1 += bflo(v.y); b1 += bfhi(v.y); }
;                 bf16_t* op = O + (row0 + t) * 2048 + h * 512 + sl * 32 + dv2;
;                 *(unsigned*)op = pk2(a0, a1); *(unsigned*)(op + 2048) = pk2(b0, b1);
;             }
;             f32x4 ndl[4]; bf16x8 nvB[4];
;             SCAN_LREAD(nbuf, nvB, ndl);
; #pragma unroll
;             for (int i = 0; i < 16; ++i) S[i] *= dl[i >> 2][i & 3];
; #pragma unroll
	s_waitcnt vmcnt(12)
	ds_write_b128 v240, v[208:211]
	global_load_dwordx4 v[208:211], v[194:195], off
	v_lshl_add_u64 v[194:195], v[194:195], 0, v[254:255]
	ds_read_b128 v[32:35], v244 offset:16384
	ds_read_b128 v[36:39], v244 offset:17408
	v_mfma_f32_32x32x16_bf16 v[16:31], v[92:95], v[48:51], 0
	v_pk_mul_f32 v[0:1], v[178:179], v[0:1]
	v_pk_mul_f32 v[2:3], v[180:181], v[2:3]
	v_pk_mul_f32 v[4:5], v[182:183], v[4:5]
	v_pk_mul_f32 v[6:7], v[184:185], v[6:7]
	v_mfma_f32_32x32x16_bf16 v[16:31], v[96:99], v[52:55], v[16:31]
	v_pk_mul_f32 v[8:9], v[186:187], v[8:9]
	v_pk_mul_f32 v[10:11], v[188:189], v[10:11]
	v_pk_mul_f32 v[12:13], v[190:191], v[12:13]
	v_pk_mul_f32 v[14:15], v[192:193], v[14:15]
	s_waitcnt lgkmcnt(0)
	v_mfma_f32_32x32x16_bf16 v[16:31], v[100:103], v[32:35], v[16:31]
	v_mfma_f32_32x32x16_bf16 v[16:31], v[104:107], v[36:39], v[16:31]
	v_mfma_f32_32x32x16_bf16 v[16:31], v[108:111], v[200:203], v[16:31]
	v_mfma_f32_32x32x16_bf16 v[0:15], v[112:115], v[144:147], v[0:15]
	v_mfma_f32_32x32x16_bf16 v[0:15], v[116:119], v[148:151], v[0:15]
	v_mfma_f32_32x32x16_bf16 v[0:15], v[120:123], v[152:155], v[0:15]
	v_mfma_f32_32x32x16_bf16 v[0:15], v[124:127], v[156:159], v[0:15]
	ds_read2st64_b64 v[212:215], v245 offset0:0 offset1:8
	ds_read2st64_b64 v[216:219], v245 offset0:16 offset1:24
	ds_read_b128 v[128:131], v246 offset:0
	global_load_dwordx4 v[112:115], v235, s[32:33]
	ds_read_b128 v[132:135], v246 offset:1024
	ds_read_b128 v[136:139], v246 offset:2048
	ds_read_b128 v[140:143], v246 offset:3072
	ds_read_b128 v[196:199], v248 offset:0
	ds_read_b128 v[162:165], v247 offset:0
	ds_read_b128 v[166:169], v247 offset:32
	global_load_dwordx4 v[116:119], v235, s[32:33] offset:1024
	ds_read_b128 v[170:173], v247 offset:64
	ds_read_b128 v[174:177], v247 offset:96
	s_waitcnt lgkmcnt(10)
	v_lshlrev_b32_e32 v229, 16, v213
	v_lshlrev_b32_e32 v228, 16, v212
	v_pk_add_f32 v[228:229], v[228:229], 0 op_sel_hi:[1,0]
	global_load_dwordx4 v[120:123], v235, s[32:33] offset:2048
	v_and_b32_e32 v231, 0xffff0000, v213
	v_and_b32_e32 v230, 0xffff0000, v212
	v_pk_add_f32 v[230:231], v[230:231], 0 op_sel_hi:[1,0]
	v_lshlrev_b32_e32 v41, 16, v215
	v_lshlrev_b32_e32 v40, 16, v214
	v_pk_add_f32 v[228:229], v[228:229], v[40:41]
	global_load_dwordx4 v[124:127], v235, s[32:33] offset:3072
	v_and_b32_e32 v215, 0xffff0000, v215
	v_and_b32_e32 v214, 0xffff0000, v214
	v_pk_add_f32 v[230:231], v[230:231], v[214:215]
	s_waitcnt lgkmcnt(9)
	v_lshlrev_b32_e32 v41, 16, v217
	v_lshlrev_b32_e32 v40, 16, v216
	global_load_dwordx4 v[92:95], v232, s[34:35] offset:-4096
	v_pk_add_f32 v[228:229], v[228:229], v[40:41]
	v_and_b32_e32 v217, 0xffff0000, v217
	v_and_b32_e32 v216, 0xffff0000, v216
	v_pk_add_f32 v[230:231], v[230:231], v[216:217]
	v_lshlrev_b32_e32 v41, 16, v219
	v_lshlrev_b32_e32 v40, 16, v218
	global_load_dwordx4 v[96:99], v232, s[34:35]
	v_pk_add_f32 v[228:229], v[228:229], v[40:41]
	v_and_b32_e32 v219, 0xffff0000, v219
	v_and_b32_e32 v218, 0xffff0000, v218
	v_pk_add_f32 v[230:231], v[230:231], v[218:219]
	v_cvt_pk_bf16_f32 v228, v228, v229
	v_cvt_pk_bf16_f32 v230, v230, v231
	global_load_dwordx4 v[100:103], v233, s[34:35] offset:-4096
	global_store_dword v249, v228, s[38:39]
	global_store_dword v250, v230, s[38:39]
	s_add_u32 s38, s38, s55
	s_addc_u32 s39, s39, s56
	v_cvt_pk_bf16_f32 v16, v16, v17
	v_cvt_pk_bf16_f32 v18, v18, v19
	global_load_dwordx4 v[104:107], v233, s[34:35]
	v_cvt_pk_bf16_f32 v20, v20, v21
	v_cvt_pk_bf16_f32 v22, v22, v23
	v_cvt_pk_bf16_f32 v24, v24, v25
	v_cvt_pk_bf16_f32 v26, v26, v27
	v_cvt_pk_bf16_f32 v28, v28, v29
	v_cvt_pk_bf16_f32 v30, v30, v31
	global_load_dwordx4 v[108:111], v251, s[36:37]
	ds_write2st64_b32 v241, v16, v20 offset0:64 offset1:66
	ds_write2st64_b32 v242, v18, v22 offset0:65 offset1:67
	ds_write2st64_b32 v241, v24, v28 offset0:68 offset1:70
	ds_write2st64_b32 v242, v26, v30 offset0:69 offset1:71
	s_add_u32 s32, s32, s53
	s_addc_u32 s33, s33, s56
	s_add_u32 s34, s34, s53
	s_addc_u32 s35, s35, s56
	s_add_u32 s36, s36, s54
	s_addc_u32 s37, s37, s56
	v_cvt_pk_bf16_f32 v48, v0, v1
	v_cvt_pk_bf16_f32 v49, v2, v3
	v_cvt_pk_bf16_f32 v50, v4, v5
	v_cvt_pk_bf16_f32 v51, v6, v7
	v_cvt_pk_bf16_f32 v52, v8, v9
	v_cvt_pk_bf16_f32 v53, v10, v11
	v_cvt_pk_bf16_f32 v54, v12, v13
	v_cvt_pk_bf16_f32 v55, v14, v15
	ds_write_b128 v243, v[48:51] offset:0
	ds_write_b128 v243, v[52:55] offset:1024
	s_waitcnt lgkmcnt(0)
	s_barrier
	s_mov_b32 s30, 4
; __device__ __forceinline__ void phase_scan(const Args& a, unsigned char* smem, int tid, int lane, int wave) {
;     ...
;             if (gc < 512) {
;                 u32x4 s0, s1;
;                 s0.x = pk2(S[0], S[1]); s0.y = pk2(S[2], S[3]); s0.z = pk2(S[4], S[5]); s0.w = pk2(S[6], S[7]);
;                 s1.x = pk2(S[8], S[9]); s1.y = pk2(S[10], S[11]); s1.z = pk2(S[12], S[13]); s1.w = pk2(S[14], S[15]);
;                 const bf16x8 sb0 = __builtin_bit_cast(bf16x8, s0), sb1 = __builtin_bit_cast(bf16x8, s1);
;                 f32x16 o0, o1;
; #pragma unroll
;                 for (int i = 0; i < 16; ++i) { o0[i] = 0.f; o1[i] = 0.f; }
;                 o0 = mfma32(qeA[0], sb0, o0); o0 = mfma32(qeA[1], sb1, o0);
;                 o1 = mfma32(qeA[2], sb0, o1); o1 = mfma32(qeA[3], sb1, o1);
;                 const int w3 = wave & 3;
;                 const bf16x8 vs = w3 == 0 ? vB[0] : (w3 == 1 ? vB[1] : (w3 == 2 ? vB[2] : vB[3]));
;                 if (wave < 4) o0 = mfma32(atA, vs, o0); else o1 = mfma32(atA, vs, o1);
;                 unsigned* rb = red + (size_t)(rbuf * 8 + wave) * 1024 + lane; unsigned* rbx = red + (size_t)(rbuf * 8 + wave) * 1024 + (lane ^ 32);
; #pragma unroll
;                 for (int i = 0; i < 8; ++i) { unsigned* w_ = (i & 1) ? rbx : rb; w_[i * 64] = pk2(o0[2 * i], o0[2 * i + 1]); w_[512 + i * 64] = pk2(o1[2 * i], o1[2 * i + 1]); }
;             }
;             SCAN_GSTORE(nbuf, gcur);
;             __syncthreads();
;             if (gc < 512) {
;                 const int tp = tid >> 4, dv2 = (tid & 15) * 2, t = tp * 2, mt = t >> 5, tl = t & 31, pi = 2 * (tl >> 3) + ((tl & 3) >> 1), ln = ((tl >> 2) & 1) * 32 + dv2;
;                 const unsigned* rp = red + (size_t)rbuf * 8192 + (mt * 8 + pi) * 64 + (ln ^ ((pi & 1) << 5));
;                 float a0 = 0.f, a1 = 0.f, b0 = 0.f, b1 = 0.f;
; #pragma unroll
;                 for (int w = 0; w < 8; ++w) { const u32x2 v = *(const u32x2*)(rp + w * 1024); a0 += bflo(v.x); b0 += bfhi(v.x); a1 += bflo(v.y); b1 += bfhi(v.y); }
;                 bf16_t* op = O + (row0 + t) * 2048 + h * 512 + sl * 32 + dv2;
;                 *(unsigned*)op = pk2(a0, a1); *(unsigned*)(op + 2048) = pk2(b0, b1);
;             }
;             f32x4 ndl[4]; bf16x8 nvB[4];
;             SCAN_LREAD(nbuf, nvB, ndl);
; #pragma unroll
;             for (int i = 0; i < 16; ++i) S[i] *= dl[i >> 2][i & 3];
; #pragma unroll
.Lscan_loopA:
	s_waitcnt vmcnt(12)
	ds_write_b128 v239, v[204:207]
	global_load_dwordx4 v[204:207], v[194:195], off
	v_lshl_add_u64 v[194:195], v[194:195], 0, v[254:255]
	ds_read_b128 v[32:35], v244 offset:0
	ds_read_b128 v[36:39], v244 offset:1024
	v_mfma_f32_32x32x16_bf16 v[16:31], v[56:59], v[48:51], 0
	v_pk_mul_f32 v[0:1], v[162:163], v[0:1]
	v_pk_mul_f32 v[2:3], v[164:165], v[2:3]
	v_pk_mul_f32 v[4:5], v[166:167], v[4:5]
	v_pk_mul_f32 v[6:7], v[168:169], v[6:7]
	v_mfma_f32_32x32x16_bf16 v[16:31], v[60:63], v[52:55], v[16:31]
	v_pk_mul_f32 v[8:9], v[170:171], v[8:9]
	v_pk_mul_f32 v[10:11], v[172:173], v[10:11]
	v_pk_mul_f32 v[12:13], v[174:175], v[12:13]
	v_pk_mul_f32 v[14:15], v[176:177], v[14:15]
	s_waitcnt lgkmcnt(0)
	v_mfma_f32_32x32x16_bf16 v[16:31], v[64:67], v[32:35], v[16:31]
	v_mfma_f32_32x32x16_bf16 v[16:31], v[68:71], v[36:39], v[16:31]
	v_mfma_f32_32x32x16_bf16 v[16:31], v[72:75], v[196:199], v[16:31]
	v_mfma_f32_32x32x16_bf16 v[0:15], v[76:79], v[128:131], v[0:15]
	v_mfma_f32_32x32x16_bf16 v[0:15], v[80:83], v[132:135], v[0:15]
	v_mfma_f32_32x32x16_bf16 v[0:15], v[84:87], v[136:139], v[0:15]
	v_mfma_f32_32x32x16_bf16 v[0:15], v[88:91], v[140:143], v[0:15]
	ds_read2st64_b64 v[212:215], v245 offset0:32 offset1:40
	ds_read2st64_b64 v[216:219], v245 offset0:48 offset1:56
	ds_read_b128 v[144:147], v246 offset:4096
	global_load_dwordx4 v[76:79], v235, s[32:33]
	ds_read_b128 v[148:151], v246 offset:5120
	ds_read_b128 v[152:155], v246 offset:6144
	ds_read_b128 v[156:159], v246 offset:7168
	ds_read_b128 v[200:203], v248 offset:4096
	ds_read_b128 v[178:181], v247 offset:1024
	ds_read_b128 v[182:185], v247 offset:1056
	global_load_dwordx4 v[80:83], v235, s[32:33] offset:1024
	ds_read_b128 v[186:189], v247 offset:1088
	ds_read_b128 v[190:193], v247 offset:1120
	s_waitcnt lgkmcnt(10)
	v_lshlrev_b32_e32 v229, 16, v213
	v_lshlrev_b32_e32 v228, 16, v212
	v_pk_add_f32 v[228:229], v[228:229], 0 op_sel_hi:[1,0]
	global_load_dwordx4 v[84:87], v235, s[32:33] offset:2048
	v_and_b32_e32 v231, 0xffff0000, v213
	v_and_b32_e32 v230, 0xffff0000, v212
	v_pk_add_f32 v[230:231], v[230:231], 0 op_sel_hi:[1,0]
	v_lshlrev_b32_e32 v41, 16, v215
	v_lshlrev_b32_e32 v40, 16, v214
	v_pk_add_f32 v[228:229], v[228:229], v[40:41]
	global_load_dwordx4 v[88:91], v235, s[32:33] offset:3072
	v_and_b32_e32 v215, 0xffff0000, v215
	v_and_b32_e32 v214, 0xffff0000, v214
	v_pk_add_f32 v[230:231], v[230:231], v[214:215]
	s_waitcnt lgkmcnt(9)
	v_lshlrev_b32_e32 v41, 16, v217
	v_lshlrev_b32_e32 v40, 16, v216
	global_load_dwordx4 v[56:59], v232, s[34:35] offset:-4096
	v_pk_add_f32 v[228:229], v[228:229], v[40:41]
	v_and_b32_e32 v217, 0xffff0000, v217
	v_and_b32_e32 v216, 0xffff0000, v216
	v_pk_add_f32 v[230:231], v[230:231], v[216:217]
	v_lshlrev_b32_e32 v41, 16, v219
	v_lshlrev_b32_e32 v40, 16, v218
	global_load_dwordx4 v[60:63], v232, s[34:35]
	v_pk_add_f32 v[228:229], v[228:229], v[40:41]
	v_and_b32_e32 v219, 0xffff0000, v219
	v_and_b32_e32 v218, 0xffff0000, v218
	v_pk_add_f32 v[230:231], v[230:231], v[218:219]
	v_cvt_pk_bf16_f32 v228, v228, v229
	v_cvt_pk_bf16_f32 v230, v230, v231
	global_load_dwordx4 v[64:67], v233, s[34:35] offset:-4096
	global_store_dword v249, v228, s[38:39]
	global_store_dword v250, v230, s[38:39]
	s_add_u32 s38, s38, s55
	s_addc_u32 s39, s39, s56
	v_cvt_pk_bf16_f32 v16, v16, v17
	v_cvt_pk_bf16_f32 v18, v18, v19
	global_load_dwordx4 v[68:71], v233, s[34:35]
	v_cvt_pk_bf16_f32 v20, v20, v21
	v_cvt_pk_bf16_f32 v22, v22, v23
	v_cvt_pk_bf16_f32 v24, v24, v25
	v_cvt_pk_bf16_f32 v26, v26, v27
	v_cvt_pk_bf16_f32 v28, v28, v29
	v_cvt_pk_bf16_f32 v30, v30, v31
	global_load_dwordx4 v[72:75], v251, s[36:37]
	ds_write2st64_b32 v241, v16, v20 offset0:0 offset1:2
	ds_write2st64_b32 v242, v18, v22 offset0:1 offset1:3
	ds_write2st64_b32 v241, v24, v28 offset0:4 offset1:6
	ds_write2st64_b32 v242, v26, v30 offset0:5 offset1:7
	s_add_u32 s32, s32, s53
	s_addc_u32 s33, s33, s56
	s_add_u32 s34, s34, s53
	s_addc_u32 s35, s35, s56
	s_add_u32 s36, s36, s54
	s_addc_u32 s37, s37, s56
	v_cvt_pk_bf16_f32 v48, v0, v1
	v_cvt_pk_bf16_f32 v49, v2, v3
	v_cvt_pk_bf16_f32 v50, v4, v5
	v_cvt_pk_bf16_f32 v51, v6, v7
	v_cvt_pk_bf16_f32 v52, v8, v9
	v_cvt_pk_bf16_f32 v53, v10, v11
	v_cvt_pk_bf16_f32 v54, v12, v13
	v_cvt_pk_bf16_f32 v55, v14, v15
	ds_write_b128 v243, v[48:51] offset:16384
	ds_write_b128 v243, v[52:55] offset:17408
	s_waitcnt lgkmcnt(0)
	s_barrier
; __device__ __forceinline__ void phase_scan(const Args& a, unsigned char* smem, int tid, int lane, int wave) {
;     ...
;             if (gc < 512) {
;                 u32x4 s0, s1;
;                 s0.x = pk2(S[0], S[1]); s0.y = pk2(S[2], S[3]); s0.z = pk2(S[4], S[5]); s0.w = pk2(S[6], S[7]);
;                 s1.x = pk2(S[8], S[9]); s1.y = pk2(S[10], S[11]); s1.z = pk2(S[12], S[13]); s1.w = pk2(S[14], S[15]);
;                 const bf16x8 sb0 = __builtin_bit_cast(bf16x8, s0), sb1 = __builtin_bit_cast(bf16x8, s1);
;                 f32x16 o0, o1;
; #pragma unroll
;                 for (int i = 0; i < 16; ++i) { o0[i] = 0.f; o1[i] = 0.f; }
;                 o0 = mfma32(qeA[0], sb0, o0); o0 = mfma32(qeA[1], sb1, o0);
;                 o1 = mfma32(qeA[2], sb0, o1); o1 = mfma32(qeA[3], sb1, o1);
;                 const int w3 = wave & 3;
;                 const bf16x8 vs = w3 == 0 ? vB[0] : (w3 == 1 ? vB[1] : (w3 == 2 ? vB[2] : vB[3]));
;                 if (wave < 4) o0 = mfma32(atA, vs, o0); else o1 = mfma32(atA, vs, o1);
;                 unsigned* rb = red + (size_t)(rbuf * 8 + wave) * 1024 + lane; unsigned* rbx = red + (size_t)(rbuf * 8 + wave) * 1024 + (lane ^ 32);
; #pragma unroll
;                 for (int i = 0; i < 8; ++i) { unsigned* w_ = (i & 1) ? rbx : rb; w_[i * 64] = pk2(o0[2 * i], o0[2 * i + 1]); w_[512 + i * 64] = pk2(o1[2 * i], o1[2 * i + 1]); }
;             }
;             SCAN_GSTORE(nbuf, gcur);
;             __syncthreads();
;             if (gc < 512) {
;                 const int tp = tid >> 4, dv2 = (tid & 15) * 2, t = tp * 2, mt = t >> 5, tl = t & 31, pi = 2 * (tl >> 3) + ((tl & 3) >> 1), ln = ((tl >> 2) & 1) * 32 + dv2;
;                 const unsigned* rp = red + (size_t)rbuf * 8192 + (mt * 8 + pi) * 64 + (ln ^ ((pi & 1) << 5));
;                 float a0 = 0.f, a1 = 0.f, b0 = 0.f, b1 = 0.f;
; #pragma unroll
;                 for (int w = 0; w < 8; ++w) { const u32x2 v = *(const u32x2*)(rp + w * 1024); a0 += bflo(v.x); b0 += bfhi(v.x); a1 += bflo(v.y); b1 += bfhi(v.y); }
;                 bf16_t* op = O + (row0 + t) * 2048 + h * 512 + sl * 32 + dv2;
;                 *(unsigned*)op = pk2(a0, a1); *(unsigned*)(op + 2048) = pk2(b0, b1);
;             }
;             f32x4 ndl[4]; bf16x8 nvB[4];
;             SCAN_LREAD(nbuf, nvB, ndl);
; #pragma unroll
;             for (int i = 0; i < 16; ++i) S[i] *= dl[i >> 2][i & 3];
; #pragma unroll
	s_waitcnt vmcnt(12)
	ds_write_b128 v240, v[208:211]
	global_load_dwordx4 v[208:211], v[194:195], off
	v_lshl_add_u64 v[194:195], v[194:195], 0, v[254:255]
	ds_read_b128 v[32:35], v244 offset:16384
	ds_read_b128 v[36:39], v244 offset:17408
	v_mfma_f32_32x32x16_bf16 v[16:31], v[92:95], v[48:51], 0
	v_pk_mul_f32 v[0:1], v[178:179], v[0:1]
	v_pk_mul_f32 v[2:3], v[180:181], v[2:3]
	v_pk_mul_f32 v[4:5], v[182:183], v[4:5]
	v_pk_mul_f32 v[6:7], v[184:185], v[6:7]
	v_mfma_f32_32x32x16_bf16 v[16:31], v[96:99], v[52:55], v[16:31]
	v_pk_mul_f32 v[8:9], v[186:187], v[8:9]
	v_pk_mul_f32 v[10:11], v[188:189], v[10:11]
	v_pk_mul_f32 v[12:13], v[190:191], v[12:13]
	v_pk_mul_f32 v[14:15], v[192:193], v[14:15]
	s_waitcnt lgkmcnt(0)
	v_mfma_f32_32x32x16_bf16 v[16:31], v[100:103], v[32:35], v[16:31]
	v_mfma_f32_32x32x16_bf16 v[16:31], v[104:107], v[36:39], v[16:31]
	v_mfma_f32_32x32x16_bf16 v[16:31], v[108:111], v[200:203], v[16:31]
	v_mfma_f32_32x32x16_bf16 v[0:15], v[112:115], v[144:147], v[0:15]
	v_mfma_f32_32x32x16_bf16 v[0:15], v[116:119], v[148:151], v[0:15]
	v_mfma_f32_32x32x16_bf16 v[0:15], v[120:123], v[152:155], v[0:15]
	v_mfma_f32_32x32x16_bf16 v[0:15], v[124:127], v[156:159], v[0:15]
	ds_read2st64_b64 v[212:215], v245 offset0:0 offset1:8
	ds_read2st64_b64 v[216:219], v245 offset0:16 offset1:24
	ds_read_b128 v[128:131], v246 offset:0
	global_load_dwordx4 v[112:115], v235, s[32:33]
	ds_read_b128 v[132:135], v246 offset:1024
	ds_read_b128 v[136:139], v246 offset:2048
	ds_read_b128 v[140:143], v246 offset:3072
	ds_read_b128 v[196:199], v248 offset:0
	ds_read_b128 v[162:165], v247 offset:0
	ds_read_b128 v[166:169], v247 offset:32
	global_load_dwordx4 v[116:119], v235, s[32:33] offset:1024
	ds_read_b128 v[170:173], v247 offset:64
	ds_read_b128 v[174:177], v247 offset:96
	s_waitcnt lgkmcnt(10)
	v_lshlrev_b32_e32 v229, 16, v213
	v_lshlrev_b32_e32 v228, 16, v212
	v_pk_add_f32 v[228:229], v[228:229], 0 op_sel_hi:[1,0]
	global_load_dwordx4 v[120:123], v235, s[32:33] offset:2048
	v_and_b32_e32 v231, 0xffff0000, v213
	v_and_b32_e32 v230, 0xffff0000, v212
	v_pk_add_f32 v[230:231], v[230:231], 0 op_sel_hi:[1,0]
	v_lshlrev_b32_e32 v41, 16, v215
	v_lshlrev_b32_e32 v40, 16, v214
	v_pk_add_f32 v[228:229], v[228:229], v[40:41]
	global_load_dwordx4 v[124:127], v235, s[32:33] offset:3072
	v_and_b32_e32 v215, 0xffff0000, v215
	v_and_b32_e32 v214, 0xffff0000, v214
	v_pk_add_f32 v[230:231], v[230:231], v[214:215]
	s_waitcnt lgkmcnt(9)
	v_lshlrev_b32_e32 v41, 16, v217
	v_lshlrev_b32_e32 v40, 16, v216
	global_load_dwordx4 v[92:95], v232, s[34:35] offset:-4096
	v_pk_add_f32 v[228:229], v[228:229], v[40:41]
	v_and_b32_e32 v217, 0xffff0000, v217
	v_and_b32_e32 v216, 0xffff0000, v216
	v_pk_add_f32 v[230:231], v[230:231], v[216:217]
	v_lshlrev_b32_e32 v41, 16, v219
	v_lshlrev_b32_e32 v40, 16, v218
	global_load_dwordx4 v[96:99], v232, s[34:35]
	v_pk_add_f32 v[228:229], v[228:229], v[40:41]
	v_and_b32_e32 v219, 0xffff0000, v219
	v_and_b32_e32 v218, 0xffff0000, v218
	v_pk_add_f32 v[230:231], v[230:231], v[218:219]
	v_cvt_pk_bf16_f32 v228, v228, v229
	v_cvt_pk_bf16_f32 v230, v230, v231
	global_load_dwordx4 v[100:103], v233, s[34:35] offset:-4096
	global_store_dword v249, v228, s[38:39]
	global_store_dword v250, v230, s[38:39]
	s_add_u32 s38, s38, s55
	s_addc_u32 s39, s39, s56
	v_cvt_pk_bf16_f32 v16, v16, v17
	v_cvt_pk_bf16_f32 v18, v18, v19
	global_load_dwordx4 v[104:107], v233, s[34:35]
	v_cvt_pk_bf16_f32 v20, v20, v21
	v_cvt_pk_bf16_f32 v22, v22, v23
	v_cvt_pk_bf16_f32 v24, v24, v25
	v_cvt_pk_bf16_f32 v26, v26, v27
	v_cvt_pk_bf16_f32 v28, v28, v29
	v_cvt_pk_bf16_f32 v30, v30, v31
	global_load_dwordx4 v[108:111], v251, s[36:37]
	ds_write2st64_b32 v241, v16, v20 offset0:64 offset1:66
	ds_write2st64_b32 v242, v18, v22 offset0:65 offset1:67
	ds_write2st64_b32 v241, v24, v28 offset0:68 offset1:70
	ds_write2st64_b32 v242, v26, v30 offset0:69 offset1:71
	s_add_u32 s32, s32, s53
	s_addc_u32 s33, s33, s56
	s_add_u32 s34, s34, s53
	s_addc_u32 s35, s35, s56
	s_add_u32 s36, s36, s54
	s_addc_u32 s37, s37, s56
	v_cvt_pk_bf16_f32 v48, v0, v1
	v_cvt_pk_bf16_f32 v49, v2, v3
	v_cvt_pk_bf16_f32 v50, v4, v5
	v_cvt_pk_bf16_f32 v51, v6, v7
	v_cvt_pk_bf16_f32 v52, v8, v9
	v_cvt_pk_bf16_f32 v53, v10, v11
	v_cvt_pk_bf16_f32 v54, v12, v13
	v_cvt_pk_bf16_f32 v55, v14, v15
	ds_write_b128 v243, v[48:51] offset:0
	ds_write_b128 v243, v[52:55] offset:1024
	s_waitcnt lgkmcnt(0)
	s_barrier
	s_add_i32 s30, s30, 2
	s_cmp_lt_u32 s30, 256
	s_cbranch_scc1 .Lscan_loopA
	s_branch .Lscan_join
; __device__ __forceinline__ void phase_scan(const Args& a, unsigned char* smem, int tid, int lane, int wave) {
;     ...
;             if (gc < 512) {
;                 u32x4 s0, s1;
;                 s0.x = pk2(S[0], S[1]); s0.y = pk2(S[2], S[3]); s0.z = pk2(S[4], S[5]); s0.w = pk2(S[6], S[7]);
;                 s1.x = pk2(S[8], S[9]); s1.y = pk2(S[10], S[11]); s1.z = pk2(S[12], S[13]); s1.w = pk2(S[14], S[15]);
;                 const bf16x8 sb0 = __builtin_bit_cast(bf16x8, s0), sb1 = __builtin_bit_cast(bf16x8, s1);
;                 f32x16 o0, o1;
; #pragma unroll
;                 for (int i = 0; i < 16; ++i) { o0[i] = 0.f; o1[i] = 0.f; }
;                 o0 = mfma32(qeA[0], sb0, o0); o0 = mfma32(qeA[1], sb1, o0);
;                 o1 = mfma32(qeA[2], sb0, o1); o1 = mfma32(qeA[3], sb1, o1);
;                 const int w3 = wave & 3;
;                 const bf16x8 vs = w3 == 0 ? vB[0] : (w3 == 1 ? vB[1] : (w3 == 2 ? vB[2] : vB[3]));
;                 if (wave < 4) o0 = mfma32(atA, vs, o0); else o1 = mfma32(atA, vs, o1);
;                 unsigned* rb = red + (size_t)(rbuf * 8 + wave) * 1024 + lane; unsigned* rbx = red + (size_t)(rbuf * 8 + wave) * 1024 + (lane ^ 32);
; #pragma unroll
;                 for (int i = 0; i < 8; ++i) { unsigned* w_ = (i & 1) ? rbx : rb; w_[i * 64] = pk2(o0[2 * i], o0[2 * i + 1]); w_[512 + i * 64] = pk2(o1[2 * i], o1[2 * i + 1]); }
;             }
;             SCAN_GSTORE(nbuf, gcur);
;             __syncthreads();
;             if (gc < 512) {
;                 const int tp = tid >> 4, dv2 = (tid & 15) * 2, t = tp * 2, mt = t >> 5, tl = t & 31, pi = 2 * (tl >> 3) + ((tl & 3) >> 1), ln = ((tl >> 2) & 1) * 32 + dv2;
;                 const unsigned* rp = red + (size_t)rbuf * 8192 + (mt * 8 + pi) * 64 + (ln ^ ((pi & 1) << 5));
;                 float a0 = 0.f, a1 = 0.f, b0 = 0.f, b1 = 0.f;
; #pragma unroll
;                 for (int w = 0; w < 8; ++w) { const u32x2 v = *(const u32x2*)(rp + w * 1024); a0 += bflo(v.x); b0 += bfhi(v.x); a1 += bflo(v.y); b1 += bfhi(v.y); }
;                 bf16_t* op = O + (row0 + t) * 2048 + h * 512 + sl * 32 + dv2;
;                 *(unsigned*)op = pk2(a0, a1); *(unsigned*)(op + 2048) = pk2(b0, b1);
;             }
;             f32x4 ndl[4]; bf16x8 nvB[4];
;             SCAN_LREAD(nbuf, nvB, ndl);
; #pragma unroll
;             for (int i = 0; i < 16; ++i) S[i] *= dl[i >> 2][i & 3];
; #pragma unroll
.Lscan_pathB:
	s_waitcnt vmcnt(10)
	ds_write_b128 v239, v[204:207]
	global_load_dwordx4 v[204:207], v[194:195], off
	v_lshl_add_u64 v[194:195], v[194:195], 0, v[254:255]
	ds_read_b128 v[32:35], v244 offset:0
	ds_read_b128 v[36:39], v244 offset:1024
	v_mfma_f32_32x32x16_bf16 v[16:31], v[56:59], v[48:51], 0
	v_pk_mul_f32 v[0:1], v[162:163], v[0:1]
	v_pk_mul_f32 v[2:3], v[164:165], v[2:3]
	v_pk_mul_f32 v[4:5], v[166:167], v[4:5]
	v_pk_mul_f32 v[6:7], v[168:169], v[6:7]
	v_mfma_f32_32x32x16_bf16 v[16:31], v[60:63], v[52:55], v[16:31]
	v_pk_mul_f32 v[8:9], v[170:171], v[8:9]
	v_pk_mul_f32 v[10:11], v[172:173], v[10:11]
	v_pk_mul_f32 v[12:13], v[174:175], v[12:13]
	v_pk_mul_f32 v[14:15], v[176:177], v[14:15]
	s_waitcnt lgkmcnt(0)
	v_mfma_f32_32x32x16_bf16 v[16:31], v[64:67], v[32:35], v[16:31]
	v_mfma_f32_32x32x16_bf16 v[16:31], v[68:71], v[36:39], v[16:31]
	v_mfma_f32_32x32x16_bf16 v[16:31], v[72:75], v[196:199], v[16:31]
	v_mfma_f32_32x32x16_bf16 v[0:15], v[76:79], v[128:131], v[0:15]
	global_load_dwordx4 v[56:59], v232, s[34:35] offset:-4096
	v_mfma_f32_32x32x16_bf16 v[0:15], v[80:83], v[132:135], v[0:15]
	global_load_dwordx4 v[60:63], v232, s[34:35]
	v_mfma_f32_32x32x16_bf16 v[0:15], v[84:87], v[136:139], v[0:15]
	global_load_dwordx4 v[64:67], v233, s[34:35] offset:-4096
	v_mfma_f32_32x32x16_bf16 v[0:15], v[88:91], v[140:143], v[0:15]
	global_load_dwordx4 v[68:71], v233, s[34:35]
	ds_read_b128 v[144:147], v246 offset:4096
	ds_read_b128 v[148:151], v246 offset:5120
	global_load_dwordx4 v[76:79], v235, s[32:33]
	ds_read_b128 v[152:155], v246 offset:6144
	ds_read_b128 v[156:159], v246 offset:7168
	ds_read_b128 v[200:203], v248 offset:4096
	ds_read_b128 v[178:181], v247 offset:1024
	global_load_dwordx4 v[80:83], v235, s[32:33] offset:1024
	ds_read_b128 v[182:185], v247 offset:1056
	ds_read_b128 v[186:189], v247 offset:1088
	ds_read_b128 v[190:193], v247 offset:1120
	v_cvt_pk_bf16_f32 v16, v16, v17
	global_load_dwordx4 v[84:87], v235, s[32:33] offset:2048
	v_cvt_pk_bf16_f32 v18, v18, v19
	v_cvt_pk_bf16_f32 v20, v20, v21
	v_cvt_pk_bf16_f32 v22, v22, v23
	v_cvt_pk_bf16_f32 v24, v24, v25
	global_load_dwordx4 v[88:91], v235, s[32:33] offset:3072
	v_cvt_pk_bf16_f32 v26, v26, v27
	v_cvt_pk_bf16_f32 v28, v28, v29
	v_cvt_pk_bf16_f32 v30, v30, v31
	ds_write2st64_b32 v241, v16, v20 offset0:0 offset1:2
	global_load_dwordx4 v[72:75], v251, s[36:37]
	ds_write2st64_b32 v242, v18, v22 offset0:1 offset1:3
	ds_write2st64_b32 v241, v24, v28 offset0:4 offset1:6
	ds_write2st64_b32 v242, v26, v30 offset0:5 offset1:7
	s_add_u32 s32, s32, s53
	s_addc_u32 s33, s33, s56
	s_add_u32 s34, s34, s53
	s_addc_u32 s35, s35, s56
	s_add_u32 s36, s36, s54
	s_addc_u32 s37, s37, s56
	v_cvt_pk_bf16_f32 v48, v0, v1
	v_cvt_pk_bf16_f32 v49, v2, v3
	v_cvt_pk_bf16_f32 v50, v4, v5
	v_cvt_pk_bf16_f32 v51, v6, v7
	v_cvt_pk_bf16_f32 v52, v8, v9
	v_cvt_pk_bf16_f32 v53, v10, v11
	v_cvt_pk_bf16_f32 v54, v12, v13
	v_cvt_pk_bf16_f32 v55, v14, v15
	ds_write_b128 v243, v[48:51] offset:16384
	ds_write_b128 v243, v[52:55] offset:17408
	s_waitcnt lgkmcnt(0)
	s_barrier
	s_waitcnt vmcnt(10)
	ds_write_b128 v240, v[208:211]
	global_load_dwordx4 v[208:211], v[194:195], off
	v_lshl_add_u64 v[194:195], v[194:195], 0, v[254:255]
	ds_read_b128 v[32:35], v244 offset:16384
	ds_read_b128 v[36:39], v244 offset:17408
	ds_read2st64_b64 v[212:215], v245 offset0:0 offset1:8
	ds_read2st64_b64 v[216:219], v245 offset0:16 offset1:24
	s_waitcnt lgkmcnt(1)
	v_lshlrev_b32_e32 v229, 16, v213
	v_lshlrev_b32_e32 v228, 16, v212
	v_pk_add_f32 v[228:229], v[228:229], 0 op_sel_hi:[1,0]
	v_and_b32_e32 v231, 0xffff0000, v213
	v_and_b32_e32 v230, 0xffff0000, v212
	v_pk_add_f32 v[230:231], v[230:231], 0 op_sel_hi:[1,0]
	v_lshlrev_b32_e32 v41, 16, v215
	v_lshlrev_b32_e32 v40, 16, v214
	v_pk_add_f32 v[228:229], v[228:229], v[40:41]
	v_and_b32_e32 v215, 0xffff0000, v215
	v_and_b32_e32 v214, 0xffff0000, v214
	v_pk_add_f32 v[230:231], v[230:231], v[214:215]
	s_waitcnt lgkmcnt(0)
	v_lshlrev_b32_e32 v41, 16, v217
	v_lshlrev_b32_e32 v40, 16, v216
	v_pk_add_f32 v[228:229], v[228:229], v[40:41]
	v_and_b32_e32 v217, 0xffff0000, v217
	v_and_b32_e32 v216, 0xffff0000, v216
	v_pk_add_f32 v[230:231], v[230:231], v[216:217]
	v_lshlrev_b32_e32 v41, 16, v219
	v_lshlrev_b32_e32 v40, 16, v218
	v_pk_add_f32 v[228:229], v[228:229], v[40:41]
	v_and_b32_e32 v219, 0xffff0000, v219
	v_and_b32_e32 v218, 0xffff0000, v218
	v_pk_add_f32 v[230:231], v[230:231], v[218:219]
	v_cvt_pk_bf16_f32 v228, v228, v229
	v_cvt_pk_bf16_f32 v230, v230, v231
	global_store_dword v249, v228, s[38:39]
	global_store_dword v250, v230, s[38:39]
	s_add_u32 s38, s38, s55
	s_addc_u32 s39, s39, s56
	v_mfma_f32_32x32x16_bf16 v[16:31], v[92:95], v[48:51], 0
	v_pk_mul_f32 v[0:1], v[178:179], v[0:1]
	v_pk_mul_f32 v[2:3], v[180:181], v[2:3]
	v_pk_mul_f32 v[4:5], v[182:183], v[4:5]
	v_pk_mul_f32 v[6:7], v[184:185], v[6:7]
	v_mfma_f32_32x32x16_bf16 v[16:31], v[96:99], v[52:55], v[16:31]
	v_pk_mul_f32 v[8:9], v[186:187], v[8:9]
	v_pk_mul_f32 v[10:11], v[188:189], v[10:11]
	v_pk_mul_f32 v[12:13], v[190:191], v[12:13]
	v_pk_mul_f32 v[14:15], v[192:193], v[14:15]
	s_waitcnt lgkmcnt(0)
; __device__ __forceinline__ void phase_scan(const Args& a, unsigned char* smem, int tid, int lane, int wave) {
;     ...
;             if (gc < 512) {
;                 u32x4 s0, s1;
;                 s0.x = pk2(S[0], S[1]); s0.y = pk2(S[2], S[3]); s0.z = pk2(S[4], S[5]); s0.w = pk2(S[6], S[7]);
;                 s1.x = pk2(S[8], S[9]); s1.y = pk2(S[10], S[11]); s1.z = pk2(S[12], S[13]); s1.w = pk2(S[14], S[15]);
;                 const bf16x8 sb0 = __builtin_bit_cast(bf16x8, s0), sb1 = __builtin_bit_cast(bf16x8, s1);
;                 f32x16 o0, o1;
; #pragma unroll
;                 for (int i = 0; i < 16; ++i) { o0[i] = 0.f; o1[i] = 0.f; }
;                 o0 = mfma32(qeA[0], sb0, o0); o0 = mfma32(qeA[1], sb1, o0);
;                 o1 = mfma32(qeA[2], sb0, o1); o1 = mfma32(qeA[3], sb1, o1);
;                 const int w3 = wave & 3;
;                 const bf16x8 vs = w3 == 0 ? vB[0] : (w3 == 1 ? vB[1] : (w3 == 2 ? vB[2] : vB[3]));
;                 if (wave < 4) o0 = mfma32(atA, vs, o0); else o1 = mfma32(atA, vs, o1);
;                 unsigned* rb = red + (size_t)(rbuf * 8 + wave) * 1024 + lane; unsigned* rbx = red + (size_t)(rbuf * 8 + wave) * 1024 + (lane ^ 32);
; #pragma unroll
;                 for (int i = 0; i < 8; ++i) { unsigned* w_ = (i & 1) ? rbx : rb; w_[i * 64] = pk2(o0[2 * i], o0[2 * i + 1]); w_[512 + i * 64] = pk2(o1[2 * i], o1[2 * i + 1]); }
;             }
;             SCAN_GSTORE(nbuf, gcur);
;             __syncthreads();
;             if (gc < 512) {
;                 const int tp = tid >> 4, dv2 = (tid & 15) * 2, t = tp * 2, mt = t >> 5, tl = t & 31, pi = 2 * (tl >> 3) + ((tl & 3) >> 1), ln = ((tl >> 2) & 1) * 32 + dv2;
;                 const unsigned* rp = red + (size_t)rbuf * 8192 + (mt * 8 + pi) * 64 + (ln ^ ((pi & 1) << 5));
;                 float a0 = 0.f, a1 = 0.f, b0 = 0.f, b1 = 0.f;
; #pragma unroll
;                 for (int w = 0; w < 8; ++w) { const u32x2 v = *(const u32x2*)(rp + w * 1024); a0 += bflo(v.x); b0 += bfhi(v.x); a1 += bflo(v.y); b1 += bfhi(v.y); }
;                 bf16_t* op = O + (row0 + t) * 2048 + h * 512 + sl * 32 + dv2;
;                 *(unsigned*)op = pk2(a0, a1); *(unsigned*)(op + 2048) = pk2(b0, b1);
;             }
;             f32x4 ndl[4]; bf16x8 nvB[4];
;             SCAN_LREAD(nbuf, nvB, ndl);
; #pragma unroll
;             for (int i = 0; i < 16; ++i) S[i] *= dl[i >> 2][i & 3];
; #pragma unroll
	v_mfma_f32_32x32x16_bf16 v[16:31], v[100:103], v[32:35], v[16:31]
	v_mfma_f32_32x32x16_bf16 v[16:31], v[104:107], v[36:39], v[16:31]
	v_mfma_f32_32x32x16_bf16 v[16:31], v[108:111], v[200:203], v[16:31]
	v_mfma_f32_32x32x16_bf16 v[0:15], v[112:115], v[144:147], v[0:15]
	global_load_dwordx4 v[92:95], v232, s[34:35] offset:-4096
	v_mfma_f32_32x32x16_bf16 v[0:15], v[116:119], v[148:151], v[0:15]
	global_load_dwordx4 v[96:99], v232, s[34:35]
	v_mfma_f32_32x32x16_bf16 v[0:15], v[120:123], v[152:155], v[0:15]
	global_load_dwordx4 v[100:103], v233, s[34:35] offset:-4096
	v_mfma_f32_32x32x16_bf16 v[0:15], v[124:127], v[156:159], v[0:15]
	global_load_dwordx4 v[104:107], v233, s[34:35]
	ds_read_b128 v[128:131], v246 offset:0
	ds_read_b128 v[132:135], v246 offset:1024
	global_load_dwordx4 v[112:115], v235, s[32:33]
	ds_read_b128 v[136:139], v246 offset:2048
	ds_read_b128 v[140:143], v246 offset:3072
	ds_read_b128 v[196:199], v248 offset:0
	ds_read_b128 v[162:165], v247 offset:0
	global_load_dwordx4 v[116:119], v235, s[32:33] offset:1024
	ds_read_b128 v[166:169], v247 offset:32
	ds_read_b128 v[170:173], v247 offset:64
	ds_read_b128 v[174:177], v247 offset:96
	v_cvt_pk_bf16_f32 v16, v16, v17
	global_load_dwordx4 v[120:123], v235, s[32:33] offset:2048
	v_cvt_pk_bf16_f32 v18, v18, v19
	v_cvt_pk_bf16_f32 v20, v20, v21
	v_cvt_pk_bf16_f32 v22, v22, v23
	v_cvt_pk_bf16_f32 v24, v24, v25
	global_load_dwordx4 v[124:127], v235, s[32:33] offset:3072
	v_cvt_pk_bf16_f32 v26, v26, v27
	v_cvt_pk_bf16_f32 v28, v28, v29
	v_cvt_pk_bf16_f32 v30, v30, v31
	ds_write2st64_b32 v241, v16, v20 offset0:64 offset1:66
	global_load_dwordx4 v[108:111], v251, s[36:37]
	ds_write2st64_b32 v242, v18, v22 offset0:65 offset1:67
	ds_write2st64_b32 v241, v24, v28 offset0:68 offset1:70
	ds_write2st64_b32 v242, v26, v30 offset0:69 offset1:71
	s_add_u32 s32, s32, s53
	s_addc_u32 s33, s33, s56
	s_add_u32 s34, s34, s53
	s_addc_u32 s35, s35, s56
	s_add_u32 s36, s36, s54
	s_addc_u32 s37, s37, s56
	v_cvt_pk_bf16_f32 v48, v0, v1
	v_cvt_pk_bf16_f32 v49, v2, v3
	v_cvt_pk_bf16_f32 v50, v4, v5
	v_cvt_pk_bf16_f32 v51, v6, v7
	v_cvt_pk_bf16_f32 v52, v8, v9
	v_cvt_pk_bf16_f32 v53, v10, v11
	v_cvt_pk_bf16_f32 v54, v12, v13
	v_cvt_pk_bf16_f32 v55, v14, v15
	ds_write_b128 v243, v[48:51] offset:0
	ds_write_b128 v243, v[52:55] offset:1024
	s_waitcnt lgkmcnt(0)
	s_barrier
	s_waitcnt vmcnt(12)
	ds_write_b128 v239, v[204:207]
	global_load_dwordx4 v[204:207], v[194:195], off
	v_lshl_add_u64 v[194:195], v[194:195], 0, v[254:255]
	ds_read_b128 v[32:35], v244 offset:0
	ds_read_b128 v[36:39], v244 offset:1024
	ds_read2st64_b64 v[212:215], v245 offset0:32 offset1:40
	ds_read2st64_b64 v[216:219], v245 offset0:48 offset1:56
	s_waitcnt lgkmcnt(1)
	v_lshlrev_b32_e32 v229, 16, v213
	v_lshlrev_b32_e32 v228, 16, v212
	v_pk_add_f32 v[228:229], v[228:229], 0 op_sel_hi:[1,0]
	v_and_b32_e32 v231, 0xffff0000, v213
	v_and_b32_e32 v230, 0xffff0000, v212
	v_pk_add_f32 v[230:231], v[230:231], 0 op_sel_hi:[1,0]
	v_lshlrev_b32_e32 v41, 16, v215
	v_lshlrev_b32_e32 v40, 16, v214
	v_pk_add_f32 v[228:229], v[228:229], v[40:41]
	v_and_b32_e32 v215, 0xffff0000, v215
	v_and_b32_e32 v214, 0xffff0000, v214
	v_pk_add_f32 v[230:231], v[230:231], v[214:215]
	s_waitcnt lgkmcnt(0)
	v_lshlrev_b32_e32 v41, 16, v217
	v_lshlrev_b32_e32 v40, 16, v216
	v_pk_add_f32 v[228:229], v[228:229], v[40:41]
	v_and_b32_e32 v217, 0xffff0000, v217
	v_and_b32_e32 v216, 0xffff0000, v216
	v_pk_add_f32 v[230:231], v[230:231], v[216:217]
	v_lshlrev_b32_e32 v41, 16, v219
	v_lshlrev_b32_e32 v40, 16, v218
	v_pk_add_f32 v[228:229], v[228:229], v[40:41]
	v_and_b32_e32 v219, 0xffff0000, v219
	v_and_b32_e32 v218, 0xffff0000, v218
	v_pk_add_f32 v[230:231], v[230:231], v[218:219]
	v_cvt_pk_bf16_f32 v228, v228, v229
	v_cvt_pk_bf16_f32 v230, v230, v231
	global_store_dword v249, v228, s[38:39]
	global_store_dword v250, v230, s[38:39]
	s_add_u32 s38, s38, s55
	s_addc_u32 s39, s39, s56
	v_mfma_f32_32x32x16_bf16 v[16:31], v[56:59], v[48:51], 0
	v_pk_mul_f32 v[0:1], v[162:163], v[0:1]
	v_pk_mul_f32 v[2:3], v[164:165], v[2:3]
	v_pk_mul_f32 v[4:5], v[166:167], v[4:5]
	v_pk_mul_f32 v[6:7], v[168:169], v[6:7]
	v_mfma_f32_32x32x16_bf16 v[16:31], v[60:63], v[52:55], v[16:31]
	v_pk_mul_f32 v[8:9], v[170:171], v[8:9]
	v_pk_mul_f32 v[10:11], v[172:173], v[10:11]
	v_pk_mul_f32 v[12:13], v[174:175], v[12:13]
	v_pk_mul_f32 v[14:15], v[176:177], v[14:15]
	s_waitcnt lgkmcnt(0)
	v_mfma_f32_32x32x16_bf16 v[16:31], v[64:67], v[32:35], v[16:31]
	v_mfma_f32_32x32x16_bf16 v[16:31], v[68:71], v[36:39], v[16:31]
	v_mfma_f32_32x32x16_bf16 v[16:31], v[72:75], v[196:199], v[16:31]
	v_mfma_f32_32x32x16_bf16 v[0:15], v[76:79], v[128:131], v[0:15]
	global_load_dwordx4 v[56:59], v232, s[34:35] offset:-4096
	v_mfma_f32_32x32x16_bf16 v[0:15], v[80:83], v[132:135], v[0:15]
	global_load_dwordx4 v[60:63], v232, s[34:35]
	v_mfma_f32_32x32x16_bf16 v[0:15], v[84:87], v[136:139], v[0:15]
	global_load_dwordx4 v[64:67], v233, s[34:35] offset:-4096
	v_mfma_f32_32x32x16_bf16 v[0:15], v[88:91], v[140:143], v[0:15]
	global_load_dwordx4 v[68:71], v233, s[34:35]
	ds_read_b128 v[144:147], v246 offset:4096
	ds_read_b128 v[148:151], v246 offset:5120
	global_load_dwordx4 v[76:79], v235, s[32:33]
	ds_read_b128 v[152:155], v246 offset:6144
	ds_read_b128 v[156:159], v246 offset:7168
	ds_read_b128 v[200:203], v248 offset:4096
	ds_read_b128 v[178:181], v247 offset:1024
	global_load_dwordx4 v[80:83], v235, s[32:33] offset:1024
	ds_read_b128 v[182:185], v247 offset:1056
	ds_read_b128 v[186:189], v247 offset:1088
	ds_read_b128 v[190:193], v247 offset:1120
	v_cvt_pk_bf16_f32 v16, v16, v17
	global_load_dwordx4 v[84:87], v235, s[32:33] offset:2048
	v_cvt_pk_bf16_f32 v18, v18, v19
	v_cvt_pk_bf16_f32 v20, v20, v21
	v_cvt_pk_bf16_f32 v22, v22, v23
	v_cvt_pk_bf16_f32 v24, v24, v25
	global_load_dwordx4 v[88:91], v235, s[32:33] offset:3072
	v_cvt_pk_bf16_f32 v26, v26, v27
	v_cvt_pk_bf16_f32 v28, v28, v29
	v_cvt_pk_bf16_f32 v30, v30, v31
	ds_write2st64_b32 v241, v16, v20 offset0:0 offset1:2
	global_load_dwordx4 v[72:75], v251, s[36:37]
	ds_write2st64_b32 v242, v18, v22 offset0:1 offset1:3
	ds_write2st64_b32 v241, v24, v28 offset0:4 offset1:6
	ds_write2st64_b32 v242, v26, v30 offset0:5 offset1:7
	s_add_u32 s32, s32, s53
	s_addc_u32 s33, s33, s56
	s_add_u32 s34, s34, s53
	s_addc_u32 s35, s35, s56
	s_add_u32 s36, s36, s54
	s_addc_u32 s37, s37, s56
	v_cvt_pk_bf16_f32 v48, v0, v1
	v_cvt_pk_bf16_f32 v49, v2, v3
	v_cvt_pk_bf16_f32 v50, v4, v5
	v_cvt_pk_bf16_f32 v51, v6, v7
	v_cvt_pk_bf16_f32 v52, v8, v9
	v_cvt_pk_bf16_f32 v53, v10, v11
	v_cvt_pk_bf16_f32 v54, v12, v13
	v_cvt_pk_bf16_f32 v55, v14, v15
	ds_write_b128 v243, v[48:51] offset:16384
	ds_write_b128 v243, v[52:55] offset:17408
	s_waitcnt lgkmcnt(0)
	s_barrier
; __device__ __forceinline__ void phase_scan(const Args& a, unsigned char* smem, int tid, int lane, int wave) {
;     ...
;             if (gc < 512) {
;                 u32x4 s0, s1;
;                 s0.x = pk2(S[0], S[1]); s0.y = pk2(S[2], S[3]); s0.z = pk2(S[4], S[5]); s0.w = pk2(S[6], S[7]);
;                 s1.x = pk2(S[8], S[9]); s1.y = pk2(S[10], S[11]); s1.z = pk2(S[12], S[13]); s1.w = pk2(S[14], S[15]);
;                 const bf16x8 sb0 = __builtin_bit_cast(bf16x8, s0), sb1 = __builtin_bit_cast(bf16x8, s1);
;                 f32x16 o0, o1;
; #pragma unroll
;                 for (int i = 0; i < 16; ++i) { o0[i] = 0.f; o1[i] = 0.f; }
;                 o0 = mfma32(qeA[0], sb0, o0); o0 = mfma32(qeA[1], sb1, o0);
;                 o1 = mfma32(qeA[2], sb0, o1); o1 = mfma32(qeA[3], sb1, o1);
;                 const int w3 = wave & 3;
;                 const bf16x8 vs = w3 == 0 ? vB[0] : (w3 == 1 ? vB[1] : (w3 == 2 ? vB[2] : vB[3]));
;                 if (wave < 4) o0 = mfma32(atA, vs, o0); else o1 = mfma32(atA, vs, o1);
;                 unsigned* rb = red + (size_t)(rbuf * 8 + wave) * 1024 + lane; unsigned* rbx = red + (size_t)(rbuf * 8 + wave) * 1024 + (lane ^ 32);
; #pragma unroll
;                 for (int i = 0; i < 8; ++i) { unsigned* w_ = (i & 1) ? rbx : rb; w_[i * 64] = pk2(o0[2 * i], o0[2 * i + 1]); w_[512 + i * 64] = pk2(o1[2 * i], o1[2 * i + 1]); }
;             }
;             SCAN_GSTORE(nbuf, gcur);
;             __syncthreads();
;             if (gc < 512) {
;                 const int tp = tid >> 4, dv2 = (tid & 15) * 2, t = tp * 2, mt = t >> 5, tl = t & 31, pi = 2 * (tl >> 3) + ((tl & 3) >> 1), ln = ((tl >> 2) & 1) * 32 + dv2;
;                 const unsigned* rp = red + (size_t)rbuf * 8192 + (mt * 8 + pi) * 64 + (ln ^ ((pi & 1) << 5));
;                 float a0 = 0.f, a1 = 0.f, b0 = 0.f, b1 = 0.f;
; #pragma unroll
;                 for (int w = 0; w < 8; ++w) { const u32x2 v = *(const u32x2*)(rp + w * 1024); a0 += bflo(v.x); b0 += bfhi(v.x); a1 += bflo(v.y); b1 += bfhi(v.y); }
;                 bf16_t* op = O + (row0 + t) * 2048 + h * 512 + sl * 32 + dv2;
;                 *(unsigned*)op = pk2(a0, a1); *(unsigned*)(op + 2048) = pk2(b0, b1);
;             }
;             f32x4 ndl[4]; bf16x8 nvB[4];
;             SCAN_LREAD(nbuf, nvB, ndl);
; #pragma unroll
;             for (int i = 0; i < 16; ++i) S[i] *= dl[i >> 2][i & 3];
; #pragma unroll
	s_waitcnt vmcnt(12)
	ds_write_b128 v240, v[208:211]
	global_load_dwordx4 v[208:211], v[194:195], off
	v_lshl_add_u64 v[194:195], v[194:195], 0, v[254:255]
	ds_read_b128 v[32:35], v244 offset:16384
	ds_read_b128 v[36:39], v244 offset:17408
	ds_read2st64_b64 v[212:215], v245 offset0:0 offset1:8
	ds_read2st64_b64 v[216:219], v245 offset0:16 offset1:24
	s_waitcnt lgkmcnt(1)
	v_lshlrev_b32_e32 v229, 16, v213
	v_lshlrev_b32_e32 v228, 16, v212
	v_pk_add_f32 v[228:229], v[228:229], 0 op_sel_hi:[1,0]
	v_and_b32_e32 v231, 0xffff0000, v213
	v_and_b32_e32 v230, 0xffff0000, v212
	v_pk_add_f32 v[230:231], v[230:231], 0 op_sel_hi:[1,0]
	v_lshlrev_b32_e32 v41, 16, v215
	v_lshlrev_b32_e32 v40, 16, v214
	v_pk_add_f32 v[228:229], v[228:229], v[40:41]
	v_and_b32_e32 v215, 0xffff0000, v215
	v_and_b32_e32 v214, 0xffff0000, v214
	v_pk_add_f32 v[230:231], v[230:231], v[214:215]
	s_waitcnt lgkmcnt(0)
	v_lshlrev_b32_e32 v41, 16, v217
	v_lshlrev_b32_e32 v40, 16, v216
	v_pk_add_f32 v[228:229], v[228:229], v[40:41]
	v_and_b32_e32 v217, 0xffff0000, v217
	v_and_b32_e32 v216, 0xffff0000, v216
	v_pk_add_f32 v[230:231], v[230:231], v[216:217]
	v_lshlrev_b32_e32 v41, 16, v219
	v_lshlrev_b32_e32 v40, 16, v218
	v_pk_add_f32 v[228:229], v[228:229], v[40:41]
	v_and_b32_e32 v219, 0xffff0000, v219
	v_and_b32_e32 v218, 0xffff0000, v218
	v_pk_add_f32 v[230:231], v[230:231], v[218:219]
	v_cvt_pk_bf16_f32 v228, v228, v229
	v_cvt_pk_bf16_f32 v230, v230, v231
	global_store_dword v249, v228, s[38:39]
	global_store_dword v250, v230, s[38:39]
	s_add_u32 s38, s38, s55
	s_addc_u32 s39, s39, s56
	v_mfma_f32_32x32x16_bf16 v[16:31], v[92:95], v[48:51], 0
	v_pk_mul_f32 v[0:1], v[178:179], v[0:1]
	v_pk_mul_f32 v[2:3], v[180:181], v[2:3]
	v_pk_mul_f32 v[4:5], v[182:183], v[4:5]
	v_pk_mul_f32 v[6:7], v[184:185], v[6:7]
	v_mfma_f32_32x32x16_bf16 v[16:31], v[96:99], v[52:55], v[16:31]
	v_pk_mul_f32 v[8:9], v[186:187], v[8:9]
	v_pk_mul_f32 v[10:11], v[188:189], v[10:11]
	v_pk_mul_f32 v[12:13], v[190:191], v[12:13]
	v_pk_mul_f32 v[14:15], v[192:193], v[14:15]
	s_waitcnt lgkmcnt(0)
	v_mfma_f32_32x32x16_bf16 v[16:31], v[100:103], v[32:35], v[16:31]
	v_mfma_f32_32x32x16_bf16 v[16:31], v[104:107], v[36:39], v[16:31]
	v_mfma_f32_32x32x16_bf16 v[16:31], v[108:111], v[200:203], v[16:31]
	v_mfma_f32_32x32x16_bf16 v[0:15], v[112:115], v[144:147], v[0:15]
	global_load_dwordx4 v[92:95], v232, s[34:35] offset:-4096
	v_mfma_f32_32x32x16_bf16 v[0:15], v[116:119], v[148:151], v[0:15]
	global_load_dwordx4 v[96:99], v232, s[34:35]
	v_mfma_f32_32x32x16_bf16 v[0:15], v[120:123], v[152:155], v[0:15]
	global_load_dwordx4 v[100:103], v233, s[34:35] offset:-4096
	v_mfma_f32_32x32x16_bf16 v[0:15], v[124:127], v[156:159], v[0:15]
	global_load_dwordx4 v[104:107], v233, s[34:35]
	ds_read_b128 v[128:131], v246 offset:0
	ds_read_b128 v[132:135], v246 offset:1024
	global_load_dwordx4 v[112:115], v235, s[32:33]
	ds_read_b128 v[136:139], v246 offset:2048
	ds_read_b128 v[140:143], v246 offset:3072
	ds_read_b128 v[196:199], v248 offset:0
	ds_read_b128 v[162:165], v247 offset:0
	global_load_dwordx4 v[116:119], v235, s[32:33] offset:1024
	ds_read_b128 v[166:169], v247 offset:32
	ds_read_b128 v[170:173], v247 offset:64
	ds_read_b128 v[174:177], v247 offset:96
	v_cvt_pk_bf16_f32 v16, v16, v17
	global_load_dwordx4 v[120:123], v235, s[32:33] offset:2048
	v_cvt_pk_bf16_f32 v18, v18, v19
	v_cvt_pk_bf16_f32 v20, v20, v21
	v_cvt_pk_bf16_f32 v22, v22, v23
	v_cvt_pk_bf16_f32 v24, v24, v25
	global_load_dwordx4 v[124:127], v235, s[32:33] offset:3072
	v_cvt_pk_bf16_f32 v26, v26, v27
	v_cvt_pk_bf16_f32 v28, v28, v29
	v_cvt_pk_bf16_f32 v30, v30, v31
	ds_write2st64_b32 v241, v16, v20 offset0:64 offset1:66
	global_load_dwordx4 v[108:111], v251, s[36:37]
	ds_write2st64_b32 v242, v18, v22 offset0:65 offset1:67
	ds_write2st64_b32 v241, v24, v28 offset0:68 offset1:70
	ds_write2st64_b32 v242, v26, v30 offset0:69 offset1:71
	s_add_u32 s32, s32, s53
	s_addc_u32 s33, s33, s56
	s_add_u32 s34, s34, s53
	s_addc_u32 s35, s35, s56
	s_add_u32 s36, s36, s54
	s_addc_u32 s37, s37, s56
	v_cvt_pk_bf16_f32 v48, v0, v1
	v_cvt_pk_bf16_f32 v49, v2, v3
	v_cvt_pk_bf16_f32 v50, v4, v5
	v_cvt_pk_bf16_f32 v51, v6, v7
	v_cvt_pk_bf16_f32 v52, v8, v9
	v_cvt_pk_bf16_f32 v53, v10, v11
	v_cvt_pk_bf16_f32 v54, v12, v13
	v_cvt_pk_bf16_f32 v55, v14, v15
	ds_write_b128 v243, v[48:51] offset:0
	ds_write_b128 v243, v[52:55] offset:1024
	s_waitcnt lgkmcnt(0)
	s_barrier
	s_mov_b32 s30, 4
; __device__ __forceinline__ void phase_scan(const Args& a, unsigned char* smem, int tid, int lane, int wave) {
;     ...
;             if (gc < 512) {
;                 u32x4 s0, s1;
;                 s0.x = pk2(S[0], S[1]); s0.y = pk2(S[2], S[3]); s0.z = pk2(S[4], S[5]); s0.w = pk2(S[6], S[7]);
;                 s1.x = pk2(S[8], S[9]); s1.y = pk2(S[10], S[11]); s1.z = pk2(S[12], S[13]); s1.w = pk2(S[14], S[15]);
;                 const bf16x8 sb0 = __builtin_bit_cast(bf16x8, s0), sb1 = __builtin_bit_cast(bf16x8, s1);
;                 f32x16 o0, o1;
; #pragma unroll
;                 for (int i = 0; i < 16; ++i) { o0[i] = 0.f; o1[i] = 0.f; }
;                 o0 = mfma32(qeA[0], sb0, o0); o0 = mfma32(qeA[1], sb1, o0);
;                 o1 = mfma32(qeA[2], sb0, o1); o1 = mfma32(qeA[3], sb1, o1);
;                 const int w3 = wave & 3;
;                 const bf16x8 vs = w3 == 0 ? vB[0] : (w3 == 1 ? vB[1] : (w3 == 2 ? vB[2] : vB[3]));
;                 if (wave < 4) o0 = mfma32(atA, vs, o0); else o1 = mfma32(atA, vs, o1);
;                 unsigned* rb = red + (size_t)(rbuf * 8 + wave) * 1024 + lane; unsigned* rbx = red + (size_t)(rbuf * 8 + wave) * 1024 + (lane ^ 32);
; #pragma unroll
;                 for (int i = 0; i < 8; ++i) { unsigned* w_ = (i & 1) ? rbx : rb; w_[i * 64] = pk2(o0[2 * i], o0[2 * i + 1]); w_[512 + i * 64] = pk2(o1[2 * i], o1[2 * i + 1]); }
;             }
;             SCAN_GSTORE(nbuf, gcur);
;             __syncthreads();
;             if (gc < 512) {
;                 const int tp = tid >> 4, dv2 = (tid & 15) * 2, t = tp * 2, mt = t >> 5, tl = t & 31, pi = 2 * (tl >> 3) + ((tl & 3) >> 1), ln = ((tl >> 2) & 1) * 32 + dv2;
;                 const unsigned* rp = red + (size_t)rbuf * 8192 + (mt * 8 + pi) * 64 + (ln ^ ((pi & 1) << 5));
;                 float a0 = 0.f, a1 = 0.f, b0 = 0.f, b1 = 0.f;
; #pragma unroll
;                 for (int w = 0; w < 8; ++w) { const u32x2 v = *(const u32x2*)(rp + w * 1024); a0 += bflo(v.x); b0 += bfhi(v.x); a1 += bflo(v.y); b1 += bfhi(v.y); }
;                 bf16_t* op = O + (row0 + t) * 2048 + h * 512 + sl * 32 + dv2;
;                 *(unsigned*)op = pk2(a0, a1); *(unsigned*)(op + 2048) = pk2(b0, b1);
;             }
;             f32x4 ndl[4]; bf16x8 nvB[4];
;             SCAN_LREAD(nbuf, nvB, ndl);
; #pragma unroll
;             for (int i = 0; i < 16; ++i) S[i] *= dl[i >> 2][i & 3];
; #pragma unroll
.Lscan_loopB:
	s_waitcnt vmcnt(12)
	ds_write_b128 v239, v[204:207]
	global_load_dwordx4 v[204:207], v[194:195], off
	v_lshl_add_u64 v[194:195], v[194:195], 0, v[254:255]
	ds_read_b128 v[32:35], v244 offset:0
	ds_read_b128 v[36:39], v244 offset:1024
	ds_read2st64_b64 v[212:215], v245 offset0:32 offset1:40
	ds_read2st64_b64 v[216:219], v245 offset0:48 offset1:56
	s_waitcnt lgkmcnt(1)
	v_lshlrev_b32_e32 v229, 16, v213
	v_lshlrev_b32_e32 v228, 16, v212
	v_pk_add_f32 v[228:229], v[228:229], 0 op_sel_hi:[1,0]
	v_and_b32_e32 v231, 0xffff0000, v213
	v_and_b32_e32 v230, 0xffff0000, v212
	v_pk_add_f32 v[230:231], v[230:231], 0 op_sel_hi:[1,0]
	v_lshlrev_b32_e32 v41, 16, v215
	v_lshlrev_b32_e32 v40, 16, v214
	v_pk_add_f32 v[228:229], v[228:229], v[40:41]
	v_and_b32_e32 v215, 0xffff0000, v215
	v_and_b32_e32 v214, 0xffff0000, v214
	v_pk_add_f32 v[230:231], v[230:231], v[214:215]
	s_waitcnt lgkmcnt(0)
	v_lshlrev_b32_e32 v41, 16, v217
	v_lshlrev_b32_e32 v40, 16, v216
	v_pk_add_f32 v[228:229], v[228:229], v[40:41]
	v_and_b32_e32 v217, 0xffff0000, v217
	v_and_b32_e32 v216, 0xffff0000, v216
	v_pk_add_f32 v[230:231], v[230:231], v[216:217]
	v_lshlrev_b32_e32 v41, 16, v219
	v_lshlrev_b32_e32 v40, 16, v218
	v_pk_add_f32 v[228:229], v[228:229], v[40:41]
	v_and_b32_e32 v219, 0xffff0000, v219
	v_and_b32_e32 v218, 0xffff0000, v218
	v_pk_add_f32 v[230:231], v[230:231], v[218:219]
	v_cvt_pk_bf16_f32 v228, v228, v229
	v_cvt_pk_bf16_f32 v230, v230, v231
	global_store_dword v249, v228, s[38:39]
	global_store_dword v250, v230, s[38:39]
	s_add_u32 s38, s38, s55
	s_addc_u32 s39, s39, s56
	v_mfma_f32_32x32x16_bf16 v[16:31], v[56:59], v[48:51], 0
	v_pk_mul_f32 v[0:1], v[162:163], v[0:1]
	v_pk_mul_f32 v[2:3], v[164:165], v[2:3]
	v_pk_mul_f32 v[4:5], v[166:167], v[4:5]
	v_pk_mul_f32 v[6:7], v[168:169], v[6:7]
	v_mfma_f32_32x32x16_bf16 v[16:31], v[60:63], v[52:55], v[16:31]
	v_pk_mul_f32 v[8:9], v[170:171], v[8:9]
	v_pk_mul_f32 v[10:11], v[172:173], v[10:11]
	v_pk_mul_f32 v[12:13], v[174:175], v[12:13]
	v_pk_mul_f32 v[14:15], v[176:177], v[14:15]
	s_waitcnt lgkmcnt(0)
	v_mfma_f32_32x32x16_bf16 v[16:31], v[64:67], v[32:35], v[16:31]
	v_mfma_f32_32x32x16_bf16 v[16:31], v[68:71], v[36:39], v[16:31]
	v_mfma_f32_32x32x16_bf16 v[16:31], v[72:75], v[196:199], v[16:31]
	v_mfma_f32_32x32x16_bf16 v[0:15], v[76:79], v[128:131], v[0:15]
	global_load_dwordx4 v[56:59], v232, s[34:35] offset:-4096
	v_mfma_f32_32x32x16_bf16 v[0:15], v[80:83], v[132:135], v[0:15]
	global_load_dwordx4 v[60:63], v232, s[34:35]
	v_mfma_f32_32x32x16_bf16 v[0:15], v[84:87], v[136:139], v[0:15]
	global_load_dwordx4 v[64:67], v233, s[34:35] offset:-4096
	v_mfma_f32_32x32x16_bf16 v[0:15], v[88:91], v[140:143], v[0:15]
	global_load_dwordx4 v[68:71], v233, s[34:35]
	ds_read_b128 v[144:147], v246 offset:4096
	ds_read_b128 v[148:151], v246 offset:5120
	global_load_dwordx4 v[76:79], v235, s[32:33]
	ds_read_b128 v[152:155], v246 offset:6144
	ds_read_b128 v[156:159], v246 offset:7168
	ds_read_b128 v[200:203], v248 offset:4096
	ds_read_b128 v[178:181], v247 offset:1024
	global_load_dwordx4 v[80:83], v235, s[32:33] offset:1024
	ds_read_b128 v[182:185], v247 offset:1056
	ds_read_b128 v[186:189], v247 offset:1088
	ds_read_b128 v[190:193], v247 offset:1120
	v_cvt_pk_bf16_f32 v16, v16, v17
	global_load_dwordx4 v[84:87], v235, s[32:33] offset:2048
	v_cvt_pk_bf16_f32 v18, v18, v19
	v_cvt_pk_bf16_f32 v20, v20, v21
	v_cvt_pk_bf16_f32 v22, v22, v23
	v_cvt_pk_bf16_f32 v24, v24, v25
	global_load_dwordx4 v[88:91], v235, s[32:33] offset:3072
	v_cvt_pk_bf16_f32 v26, v26, v27
	v_cvt_pk_bf16_f32 v28, v28, v29
	v_cvt_pk_bf16_f32 v30, v30, v31
	ds_write2st64_b32 v241, v16, v20 offset0:0 offset1:2
	global_load_dwordx4 v[72:75], v251, s[36:37]
	ds_write2st64_b32 v242, v18, v22 offset0:1 offset1:3
	ds_write2st64_b32 v241, v24, v28 offset0:4 offset1:6
	ds_write2st64_b32 v242, v26, v30 offset0:5 offset1:7
	s_add_u32 s32, s32, s53
	s_addc_u32 s33, s33, s56
	s_add_u32 s34, s34, s53
	s_addc_u32 s35, s35, s56
	s_add_u32 s36, s36, s54
	s_addc_u32 s37, s37, s56
	v_cvt_pk_bf16_f32 v48, v0, v1
	v_cvt_pk_bf16_f32 v49, v2, v3
	v_cvt_pk_bf16_f32 v50, v4, v5
	v_cvt_pk_bf16_f32 v51, v6, v7
	v_cvt_pk_bf16_f32 v52, v8, v9
	v_cvt_pk_bf16_f32 v53, v10, v11
	v_cvt_pk_bf16_f32 v54, v12, v13
	v_cvt_pk_bf16_f32 v55, v14, v15
	ds_write_b128 v243, v[48:51] offset:16384
	ds_write_b128 v243, v[52:55] offset:17408
	s_waitcnt lgkmcnt(0)
	s_barrier
; __device__ __forceinline__ void phase_scan(const Args& a, unsigned char* smem, int tid, int lane, int wave) {
;     ...
;             if (gc < 512) {
;                 u32x4 s0, s1;
;                 s0.x = pk2(S[0], S[1]); s0.y = pk2(S[2], S[3]); s0.z = pk2(S[4], S[5]); s0.w = pk2(S[6], S[7]);
;                 s1.x = pk2(S[8], S[9]); s1.y = pk2(S[10], S[11]); s1.z = pk2(S[12], S[13]); s1.w = pk2(S[14], S[15]);
;                 const bf16x8 sb0 = __builtin_bit_cast(bf16x8, s0), sb1 = __builtin_bit_cast(bf16x8, s1);
;                 f32x16 o0, o1;
; #pragma unroll
;                 for (int i = 0; i < 16; ++i) { o0[i] = 0.f; o1[i] = 0.f; }
;                 o0 = mfma32(qeA[0], sb0, o0); o0 = mfma32(qeA[1], sb1, o0);
;                 o1 = mfma32(qeA[2], sb0, o1); o1 = mfma32(qeA[3], sb1, o1);
;                 const int w3 = wave & 3;
;                 const bf16x8 vs = w3 == 0 ? vB[0] : (w3 == 1 ? vB[1] : (w3 == 2 ? vB[2] : vB[3]));
;                 if (wave < 4) o0 = mfma32(atA, vs, o0); else o1 = mfma32(atA, vs, o1);
;                 unsigned* rb = red + (size_t)(rbuf * 8 + wave) * 1024 + lane; unsigned* rbx = red + (size_t)(rbuf * 8 + wave) * 1024 + (lane ^ 32);
; #pragma unroll
;                 for (int i = 0; i < 8; ++i) { unsigned* w_ = (i & 1) ? rbx : rb; w_[i * 64] = pk2(o0[2 * i], o0[2 * i + 1]); w_[512 + i * 64] = pk2(o1[2 * i], o1[2 * i + 1]); }
;             }
;             SCAN_GSTORE(nbuf, gcur);
;             __syncthreads();
;             if (gc < 512) {
;                 const int tp = tid >> 4, dv2 = (tid & 15) * 2, t = tp * 2, mt = t >> 5, tl = t & 31, pi = 2 * (tl >> 3) + ((tl & 3) >> 1), ln = ((tl >> 2) & 1) * 32 + dv2;
;                 const unsigned* rp = red + (size_t)rbuf * 8192 + (mt * 8 + pi) * 64 + (ln ^ ((pi & 1) << 5));
;                 float a0 = 0.f, a1 = 0.f, b0 = 0.f, b1 = 0.f;
; #pragma unroll
;                 for (int w = 0; w < 8; ++w) { const u32x2 v = *(const u32x2*)(rp + w * 1024); a0 += bflo(v.x); b0 += bfhi(v.x); a1 += bflo(v.y); b1 += bfhi(v.y); }
;                 bf16_t* op = O + (row0 + t) * 2048 + h * 512 + sl * 32 + dv2;
;                 *(unsigned*)op = pk2(a0, a1); *(unsigned*)(op + 2048) = pk2(b0, b1);
;             }
;             f32x4 ndl[4]; bf16x8 nvB[4];
;             SCAN_LREAD(nbuf, nvB, ndl);
; #pragma unroll
;             for (int i = 0; i < 16; ++i) S[i] *= dl[i >> 2][i & 3];
; #pragma unroll
	s_waitcnt vmcnt(12)
	ds_write_b128 v240, v[208:211]
	global_load_dwordx4 v[208:211], v[194:195], off
	v_lshl_add_u64 v[194:195], v[194:195], 0, v[254:255]
	ds_read_b128 v[32:35], v244 offset:16384
	ds_read_b128 v[36:39], v244 offset:17408
	ds_read2st64_b64 v[212:215], v245 offset0:0 offset1:8
	ds_read2st64_b64 v[216:219], v245 offset0:16 offset1:24
	s_waitcnt lgkmcnt(1)
	v_lshlrev_b32_e32 v229, 16, v213
	v_lshlrev_b32_e32 v228, 16, v212
	v_pk_add_f32 v[228:229], v[228:229], 0 op_sel_hi:[1,0]
	v_and_b32_e32 v231, 0xffff0000, v213
	v_and_b32_e32 v230, 0xffff0000, v212
	v_pk_add_f32 v[230:231], v[230:231], 0 op_sel_hi:[1,0]
	v_lshlrev_b32_e32 v41, 16, v215
	v_lshlrev_b32_e32 v40, 16, v214
	v_pk_add_f32 v[228:229], v[228:229], v[40:41]
	v_and_b32_e32 v215, 0xffff0000, v215
	v_and_b32_e32 v214, 0xffff0000, v214
	v_pk_add_f32 v[230:231], v[230:231], v[214:215]
	s_waitcnt lgkmcnt(0)
	v_lshlrev_b32_e32 v41, 16, v217
	v_lshlrev_b32_e32 v40, 16, v216
	v_pk_add_f32 v[228:229], v[228:229], v[40:41]
	v_and_b32_e32 v217, 0xffff0000, v217
	v_and_b32_e32 v216, 0xffff0000, v216
	v_pk_add_f32 v[230:231], v[230:231], v[216:217]
	v_lshlrev_b32_e32 v41, 16, v219
	v_lshlrev_b32_e32 v40, 16, v218
	v_pk_add_f32 v[228:229], v[228:229], v[40:41]
	v_and_b32_e32 v219, 0xffff0000, v219
	v_and_b32_e32 v218, 0xffff0000, v218
	v_pk_add_f32 v[230:231], v[230:231], v[218:219]
	v_cvt_pk_bf16_f32 v228, v228, v229
	v_cvt_pk_bf16_f32 v230, v230, v231
	global_store_dword v249, v228, s[38:39]
	global_store_dword v250, v230, s[38:39]
	s_add_u32 s38, s38, s55
	s_addc_u32 s39, s39, s56
	v_mfma_f32_32x32x16_bf16 v[16:31], v[92:95], v[48:51], 0
	v_pk_mul_f32 v[0:1], v[178:179], v[0:1]
	v_pk_mul_f32 v[2:3], v[180:181], v[2:3]
	v_pk_mul_f32 v[4:5], v[182:183], v[4:5]
	v_pk_mul_f32 v[6:7], v[184:185], v[6:7]
	v_mfma_f32_32x32x16_bf16 v[16:31], v[96:99], v[52:55], v[16:31]
	v_pk_mul_f32 v[8:9], v[186:187], v[8:9]
	v_pk_mul_f32 v[10:11], v[188:189], v[10:11]
	v_pk_mul_f32 v[12:13], v[190:191], v[12:13]
	v_pk_mul_f32 v[14:15], v[192:193], v[14:15]
	s_waitcnt lgkmcnt(0)
	v_mfma_f32_32x32x16_bf16 v[16:31], v[100:103], v[32:35], v[16:31]
	v_mfma_f32_32x32x16_bf16 v[16:31], v[104:107], v[36:39], v[16:31]
	v_mfma_f32_32x32x16_bf16 v[16:31], v[108:111], v[200:203], v[16:31]
	v_mfma_f32_32x32x16_bf16 v[0:15], v[112:115], v[144:147], v[0:15]
	global_load_dwordx4 v[92:95], v232, s[34:35] offset:-4096
	v_mfma_f32_32x32x16_bf16 v[0:15], v[116:119], v[148:151], v[0:15]
	global_load_dwordx4 v[96:99], v232, s[34:35]
	v_mfma_f32_32x32x16_bf16 v[0:15], v[120:123], v[152:155], v[0:15]
	global_load_dwordx4 v[100:103], v233, s[34:35] offset:-4096
	v_mfma_f32_32x32x16_bf16 v[0:15], v[124:127], v[156:159], v[0:15]
	global_load_dwordx4 v[104:107], v233, s[34:35]
	ds_read_b128 v[128:131], v246 offset:0
	ds_read_b128 v[132:135], v246 offset:1024
	global_load_dwordx4 v[112:115], v235, s[32:33]
	ds_read_b128 v[136:139], v246 offset:2048
	ds_read_b128 v[140:143], v246 offset:3072
	ds_read_b128 v[196:199], v248 offset:0
	ds_read_b128 v[162:165], v247 offset:0
	global_load_dwordx4 v[116:119], v235, s[32:33] offset:1024
	ds_read_b128 v[166:169], v247 offset:32
	ds_read_b128 v[170:173], v247 offset:64
	ds_read_b128 v[174:177], v247 offset:96
	v_cvt_pk_bf16_f32 v16, v16, v17
	global_load_dwordx4 v[120:123], v235, s[32:33] offset:2048
	v_cvt_pk_bf16_f32 v18, v18, v19
	v_cvt_pk_bf16_f32 v20, v20, v21
	v_cvt_pk_bf16_f32 v22, v22, v23
	v_cvt_pk_bf16_f32 v24, v24, v25
	global_load_dwordx4 v[124:127], v235, s[32:33] offset:3072
	v_cvt_pk_bf16_f32 v26, v26, v27
	v_cvt_pk_bf16_f32 v28, v28, v29
	v_cvt_pk_bf16_f32 v30, v30, v31
	ds_write2st64_b32 v241, v16, v20 offset0:64 offset1:66
	global_load_dwordx4 v[108:111], v251, s[36:37]
	ds_write2st64_b32 v242, v18, v22 offset0:65 offset1:67
	ds_write2st64_b32 v241, v24, v28 offset0:68 offset1:70
	ds_write2st64_b32 v242, v26, v30 offset0:69 offset1:71
	s_add_u32 s32, s32, s53
	s_addc_u32 s33, s33, s56
	s_add_u32 s34, s34, s53
	s_addc_u32 s35, s35, s56
	s_add_u32 s36, s36, s54
	s_addc_u32 s37, s37, s56
	v_cvt_pk_bf16_f32 v48, v0, v1
	v_cvt_pk_bf16_f32 v49, v2, v3
	v_cvt_pk_bf16_f32 v50, v4, v5
	v_cvt_pk_bf16_f32 v51, v6, v7
	v_cvt_pk_bf16_f32 v52, v8, v9
	v_cvt_pk_bf16_f32 v53, v10, v11
	v_cvt_pk_bf16_f32 v54, v12, v13
	v_cvt_pk_bf16_f32 v55, v14, v15
	ds_write_b128 v243, v[48:51] offset:0
	ds_write_b128 v243, v[52:55] offset:1024
	s_waitcnt lgkmcnt(0)
	s_barrier
	s_add_i32 s30, s30, 2
	s_cmp_lt_u32 s30, 256
	s_cbranch_scc1 .Lscan_loopB
.Lscan_join:
	ds_read2st64_b64 v[212:215], v245 offset0:32 offset1:40
	ds_read2st64_b64 v[216:219], v245 offset0:48 offset1:56
	s_waitcnt lgkmcnt(1)
	v_lshlrev_b32_e32 v229, 16, v213
	v_lshlrev_b32_e32 v228, 16, v212
	v_pk_add_f32 v[228:229], v[228:229], 0 op_sel_hi:[1,0]
	v_and_b32_e32 v231, 0xffff0000, v213
	v_and_b32_e32 v230, 0xffff0000, v212
	v_pk_add_f32 v[230:231], v[230:231], 0 op_sel_hi:[1,0]
	v_lshlrev_b32_e32 v41, 16, v215
	v_lshlrev_b32_e32 v40, 16, v214
	v_pk_add_f32 v[228:229], v[228:229], v[40:41]
	v_and_b32_e32 v215, 0xffff0000, v215
	v_and_b32_e32 v214, 0xffff0000, v214
	v_pk_add_f32 v[230:231], v[230:231], v[214:215]
	s_waitcnt lgkmcnt(0)
	v_lshlrev_b32_e32 v41, 16, v217
	v_lshlrev_b32_e32 v40, 16, v216
	v_pk_add_f32 v[228:229], v[228:229], v[40:41]
	v_and_b32_e32 v217, 0xffff0000, v217
	v_and_b32_e32 v216, 0xffff0000, v216
	v_pk_add_f32 v[230:231], v[230:231], v[216:217]
	v_lshlrev_b32_e32 v41, 16, v219
	v_lshlrev_b32_e32 v40, 16, v218
	v_pk_add_f32 v[228:229], v[228:229], v[40:41]
	v_and_b32_e32 v219, 0xffff0000, v219
	v_and_b32_e32 v218, 0xffff0000, v218
	v_pk_add_f32 v[230:231], v[230:231], v[218:219]
	v_cvt_pk_bf16_f32 v228, v228, v229
	v_cvt_pk_bf16_f32 v230, v230, v231
	global_store_dword v249, v228, s[38:39]
	global_store_dword v250, v230, s[38:39]
	s_add_u32 s38, s38, s55
	s_addc_u32 s39, s39, s56
	s_waitcnt vmcnt(0) lgkmcnt(0)
	s_barrier
